# experiment: nt stores for P8 final outputs and late-converted weights
# speedup vs baseline: 1.0366x; 1.0112x over previous
.LBB0_514:
	v_mul_u32_u24_e32 v2, s24, v1
	v_mul_u32_u24_e32 v4, s24, v91
	v_mul_u32_u24_e32 v22, s24, v92
	v_mul_u32_u24_e32 v24, s24, v93
	v_mul_u32_u24_e32 v42, s24, v77
	v_mul_u32_u24_e32 v44, s24, v88
	v_mul_u32_u24_e32 v58, s24, v89
	v_mul_u32_u24_e32 v60, s24, v90
	v_lshlrev_b32_e32 v2, 2, v2
	v_mov_b32_e32 v3, v75
	v_lshlrev_b32_e32 v4, 2, v4
	v_mov_b32_e32 v5, v75
	v_lshlrev_b32_e32 v22, 2, v22
	v_mov_b32_e32 v23, v75
	v_lshlrev_b32_e32 v24, 2, v24
	v_mov_b32_e32 v25, v75
	v_lshlrev_b32_e32 v42, 2, v42
	v_mov_b32_e32 v43, v75
	v_lshlrev_b32_e32 v44, 2, v44
	v_mov_b32_e32 v45, v75
	v_lshlrev_b32_e32 v58, 2, v58
	v_mov_b32_e32 v59, v75
	v_lshlrev_b32_e32 v60, 2, v60
	v_mov_b32_e32 v61, v75
	v_lshl_add_u64 v[2:3], s[22:23], 0, v[2:3]
	v_mov_b32_e32 v87, v75
	v_lshl_add_u64 v[4:5], s[22:23], 0, v[4:5]
	v_lshl_add_u64 v[22:23], s[22:23], 0, v[22:23]
	v_lshl_add_u64 v[24:25], s[22:23], 0, v[24:25]
	v_lshl_add_u64 v[42:43], s[22:23], 0, v[42:43]
	v_lshl_add_u64 v[44:45], s[22:23], 0, v[44:45]
	v_lshl_add_u64 v[58:59], s[22:23], 0, v[58:59]
	v_lshl_add_u64 v[60:61], s[22:23], 0, v[60:61]
	v_lshl_add_u64 v[2:3], v[2:3], 0, v[86:87]
	v_lshl_add_u64 v[10:11], v[4:5], 0, v[86:87]
	v_lshl_add_u64 v[22:23], v[22:23], 0, v[86:87]
	v_lshl_add_u64 v[26:27], v[24:25], 0, v[86:87]
	v_lshl_add_u64 v[42:43], v[42:43], 0, v[86:87]
	v_lshl_add_u64 v[46:47], v[44:45], 0, v[86:87]
	v_lshl_add_u64 v[58:59], v[58:59], 0, v[86:87]
	v_lshl_add_u64 v[62:63], v[60:61], 0, v[86:87]
	global_load_dwordx4 v[2:5], v[2:3], off nt
	s_nop 0
	global_load_dwordx4 v[10:13], v[10:11], off nt
	s_nop 0
	global_load_dwordx4 v[22:25], v[22:23], off nt
	s_nop 0
	global_load_dwordx4 v[26:29], v[26:27], off nt
	s_nop 0
	global_load_dwordx4 v[42:45], v[42:43], off nt
	s_nop 0
	global_load_dwordx4 v[46:49], v[46:47], off nt
	s_nop 0
	global_load_dwordx4 v[58:61], v[58:59], off nt
	s_nop 0
	global_load_dwordx4 v[62:65], v[62:63], off nt
	s_waitcnt vmcnt(19)
	ds_write2_b32 v95, v14, v15 offset1:1
	ds_write2_b32 v95, v16, v17 offset0:2 offset1:3
	s_waitcnt vmcnt(18)
	ds_write2_b32 v96, v6, v7 offset1:1
	ds_write2_b32 v97, v8, v9 offset1:1
	s_waitcnt vmcnt(17)
	ds_write2_b32 v98, v30, v31 offset1:1
	ds_write2_b32 v99, v32, v33 offset1:1
	s_waitcnt vmcnt(16)
	ds_write2_b32 v100, v18, v19 offset1:1
	ds_write2_b32 v101, v20, v21 offset1:1
	s_waitcnt vmcnt(15)
	ds_write2_b32 v102, v38, v39 offset1:1
	ds_write2_b32 v103, v40, v41 offset1:1
	s_waitcnt vmcnt(14)
	ds_write2_b32 v104, v34, v35 offset1:1
	ds_write2_b32 v105, v36, v37 offset1:1
	s_waitcnt vmcnt(13)
	ds_write2_b32 v106, v54, v55 offset1:1
	ds_write2_b32 v107, v56, v57 offset1:1
	s_waitcnt vmcnt(12)
	ds_write2_b32 v108, v50, v51 offset1:1
	ds_write2_b32 v109, v52, v53 offset1:1
	s_waitcnt lgkmcnt(0)
	ds_read2_b32 v[14:15], v94 offset1:8
	ds_read2_b32 v[18:19], v94 offset0:33 offset1:41
	ds_read2_b32 v[20:21], v94 offset0:66 offset1:74
	ds_read2_b32 v[30:31], v94 offset0:99 offset1:107
	ds_read2_b32 v[32:33], v94 offset0:132 offset1:140
	s_waitcnt lgkmcnt(4)
	v_bfe_u32 v6, v14, 16, 1
	v_add3_u32 v6, v14, v6, s28
	s_waitcnt lgkmcnt(3)
	v_bfe_u32 v7, v18, 16, 1
	v_lshrrev_b32_e32 v6, 16, v6
	v_add3_u32 v7, v18, v7, s28
	ds_read2_b32 v[34:35], v94 offset0:165 offset1:173
	v_and_or_b32 v6, v7, s29, v6
	s_waitcnt lgkmcnt(3)
	v_bfe_u32 v7, v20, 16, 1
	v_add3_u32 v7, v20, v7, s28
	s_waitcnt lgkmcnt(2)
	v_bfe_u32 v8, v30, 16, 1
	ds_read2_b32 v[36:37], v94 offset0:198 offset1:206
	v_lshrrev_b32_e32 v7, 16, v7
	v_add3_u32 v8, v30, v8, s28
	ds_read2_b32 v[38:39], v94 offset0:231 offset1:239
	s_lshl_b64 s[16:17], s[16:17], 12
	v_and_or_b32 v7, v8, s29, v7
	s_waitcnt lgkmcnt(3)
	v_bfe_u32 v8, v32, 16, 1
	s_add_u32 s20, s20, s16
	v_add3_u32 v8, v32, v8, s28
	s_waitcnt lgkmcnt(2)
	v_bfe_u32 v9, v34, 16, 1
	s_addc_u32 s21, s21, s17
	s_lshl_b64 s[16:17], s[0:1], 1
	v_lshrrev_b32_e32 v8, 16, v8
	v_add3_u32 v9, v34, v9, s28
	s_add_u32 s16, s20, s16
	v_and_or_b32 v8, v9, s29, v8
	s_waitcnt lgkmcnt(1)
	v_bfe_u32 v9, v36, 16, 1
	s_addc_u32 s17, s21, s17
	v_add3_u32 v9, v36, v9, s28
	s_waitcnt lgkmcnt(0)
	v_bfe_u32 v14, v38, 16, 1
	v_lshl_add_u64 v[16:17], s[16:17], 0, v[74:75]
	v_lshrrev_b32_e32 v9, 16, v9
	v_add3_u32 v14, v38, v14, s28
	v_and_or_b32 v9, v14, s29, v9
	v_lshl_add_u64 v[40:41], v[16:17], 0, v[78:79]
	global_store_dwordx4 v[40:41], v[6:9], off nt
	v_bfe_u32 v14, v39, 16, 1
	v_add3_u32 v18, v39, v14, s28
	v_bfe_u32 v6, v15, 16, 1
	v_add3_u32 v6, v15, v6, s28
	v_bfe_u32 v7, v19, 16, 1
	v_lshrrev_b32_e32 v6, 16, v6
	v_add3_u32 v7, v19, v7, s28
	v_and_or_b32 v6, v7, s29, v6
	v_bfe_u32 v7, v21, 16, 1
	v_add3_u32 v7, v21, v7, s28
	v_bfe_u32 v8, v31, 16, 1
	v_lshrrev_b32_e32 v7, 16, v7
	v_add3_u32 v8, v31, v8, s28
	v_and_or_b32 v7, v8, s29, v7
	v_bfe_u32 v8, v33, 16, 1
	v_add3_u32 v8, v33, v8, s28
	v_bfe_u32 v9, v35, 16, 1
	v_lshrrev_b32_e32 v8, 16, v8
	v_add3_u32 v9, v35, v9, s28
	v_and_or_b32 v8, v9, s29, v8
	v_bfe_u32 v9, v37, 16, 1
	v_add3_u32 v9, v37, v9, s28
	v_lshrrev_b32_e32 v9, 16, v9
	ds_read2_b32 v[14:15], v94 offset0:16 offset1:24
	v_and_or_b32 v9, v18, s29, v9
	v_lshl_add_u64 v[18:19], v[16:17], 0, v[80:81]
	global_store_dwordx4 v[18:19], v[6:9], off nt
	ds_read2_b32 v[18:19], v94 offset0:49 offset1:57
	ds_read2_b32 v[20:21], v94 offset0:82 offset1:90
	ds_read2_b32 v[30:31], v94 offset0:115 offset1:123
	s_waitcnt lgkmcnt(3)
	v_bfe_u32 v6, v14, 16, 1
	v_add3_u32 v6, v14, v6, s28
	s_waitcnt lgkmcnt(2)
	v_bfe_u32 v7, v18, 16, 1
	ds_read2_b32 v[32:33], v94 offset0:148 offset1:156
	v_lshrrev_b32_e32 v6, 16, v6
	v_add3_u32 v7, v18, v7, s28
	ds_read2_b32 v[34:35], v94 offset0:181 offset1:189
	v_and_or_b32 v6, v7, s29, v6
	s_waitcnt lgkmcnt(3)
	v_bfe_u32 v7, v20, 16, 1
	v_add3_u32 v7, v20, v7, s28
	s_waitcnt lgkmcnt(2)
	v_bfe_u32 v8, v30, 16, 1
	ds_read2_b32 v[36:37], v94 offset0:214 offset1:222
	v_lshrrev_b32_e32 v7, 16, v7
	v_add3_u32 v8, v30, v8, s28
	ds_read2_b32 v[38:39], v94 offset0:247 offset1:255
	v_and_or_b32 v7, v8, s29, v7
	s_waitcnt lgkmcnt(3)
	v_bfe_u32 v8, v32, 16, 1
	v_add3_u32 v8, v32, v8, s28
	s_waitcnt lgkmcnt(2)
	v_bfe_u32 v9, v34, 16, 1
	v_lshrrev_b32_e32 v8, 16, v8
	v_add3_u32 v9, v34, v9, s28
	v_and_or_b32 v8, v9, s29, v8
	s_waitcnt lgkmcnt(1)
	v_bfe_u32 v9, v36, 16, 1
	v_add3_u32 v9, v36, v9, s28
	s_waitcnt lgkmcnt(0)
	v_bfe_u32 v14, v38, 16, 1
	v_lshrrev_b32_e32 v9, 16, v9
	v_add3_u32 v14, v38, v14, s28
	v_and_or_b32 v9, v14, s29, v9
	v_lshl_add_u64 v[40:41], v[16:17], 0, v[82:83]
	global_store_dwordx4 v[40:41], v[6:9], off nt
	v_bfe_u32 v14, v39, 16, 1
	v_add3_u32 v14, v39, v14, s28
	v_bfe_u32 v6, v15, 16, 1
	v_add3_u32 v6, v15, v6, s28
	v_bfe_u32 v7, v19, 16, 1
	v_lshrrev_b32_e32 v6, 16, v6
	v_add3_u32 v7, v19, v7, s28
	v_and_or_b32 v6, v7, s29, v6
	v_bfe_u32 v7, v21, 16, 1
	v_add3_u32 v7, v21, v7, s28
	v_bfe_u32 v8, v31, 16, 1
	v_lshrrev_b32_e32 v7, 16, v7
	v_add3_u32 v8, v31, v8, s28
	v_and_or_b32 v7, v8, s29, v7
	v_bfe_u32 v8, v33, 16, 1
	v_add3_u32 v8, v33, v8, s28
	v_bfe_u32 v9, v35, 16, 1
	v_lshrrev_b32_e32 v8, 16, v8
	v_add3_u32 v9, v35, v9, s28
	v_and_or_b32 v8, v9, s29, v8
	v_bfe_u32 v9, v37, 16, 1
	v_add3_u32 v9, v37, v9, s28
	v_lshrrev_b32_e32 v9, 16, v9
	v_and_or_b32 v9, v14, s29, v9
	v_lshl_add_u64 v[14:15], v[16:17], 0, v[84:85]
	global_store_dwordx4 v[14:15], v[6:9], off nt
	s_waitcnt lgkmcnt(0)
	s_waitcnt vmcnt(11)
	ds_write2_b32 v95, v2, v3 offset1:1
	ds_write2_b32 v95, v4, v5 offset0:2 offset1:3
	s_waitcnt vmcnt(10)
	ds_write2_b32 v96, v10, v11 offset1:1
	ds_write2_b32 v97, v12, v13 offset1:1
	s_waitcnt vmcnt(9)
	ds_write2_b32 v98, v22, v23 offset1:1
	ds_write2_b32 v99, v24, v25 offset1:1
	s_waitcnt vmcnt(8)
	ds_write2_b32 v100, v26, v27 offset1:1
	ds_write2_b32 v101, v28, v29 offset1:1
	s_waitcnt vmcnt(7)
	ds_write2_b32 v102, v42, v43 offset1:1
	ds_write2_b32 v103, v44, v45 offset1:1
	s_waitcnt vmcnt(6)
	ds_write2_b32 v104, v46, v47 offset1:1
	ds_write2_b32 v105, v48, v49 offset1:1
	s_waitcnt vmcnt(5)
	ds_write2_b32 v106, v58, v59 offset1:1
	ds_write2_b32 v107, v60, v61 offset1:1
	s_waitcnt vmcnt(4)
	ds_write2_b32 v108, v62, v63 offset1:1
	ds_write2_b32 v109, v64, v65 offset1:1
	s_waitcnt lgkmcnt(0)
	ds_read2_b32 v[6:7], v94 offset1:8
	ds_read2_b32 v[10:11], v94 offset0:33 offset1:41
	ds_read2_b32 v[12:13], v94 offset0:66 offset1:74
	ds_read2_b32 v[14:15], v94 offset0:99 offset1:107
	ds_read2_b32 v[16:17], v94 offset0:132 offset1:140
	s_waitcnt lgkmcnt(4)
	v_bfe_u32 v2, v6, 16, 1
	v_add3_u32 v2, v6, v2, s28
	s_waitcnt lgkmcnt(3)
	v_bfe_u32 v3, v10, 16, 1
	v_lshrrev_b32_e32 v2, 16, v2
	v_add3_u32 v3, v10, v3, s28
	ds_read2_b32 v[18:19], v94 offset0:165 offset1:173
	v_and_or_b32 v2, v3, s29, v2
	s_waitcnt lgkmcnt(3)
	v_bfe_u32 v3, v12, 16, 1
	v_add3_u32 v3, v12, v3, s28
	s_waitcnt lgkmcnt(2)
	v_bfe_u32 v4, v14, 16, 1
	ds_read2_b32 v[20:21], v94 offset0:198 offset1:206
	v_lshrrev_b32_e32 v3, 16, v3
	v_add3_u32 v4, v14, v4, s28
	ds_read2_b32 v[22:23], v94 offset0:231 offset1:239
	s_lshl_b64 s[14:15], s[14:15], 12
	v_and_or_b32 v3, v4, s29, v3
	s_waitcnt lgkmcnt(3)
	v_bfe_u32 v4, v16, 16, 1
	s_add_u32 s0, s18, s14
	v_add3_u32 v4, v16, v4, s28
	s_waitcnt lgkmcnt(2)
	v_bfe_u32 v5, v18, 16, 1
	s_addc_u32 s14, s19, s15
	s_lshl_b64 s[6:7], s[6:7], 1
	v_lshrrev_b32_e32 v4, 16, v4
	v_add3_u32 v5, v18, v5, s28
	s_add_u32 s6, s0, s6
	v_and_or_b32 v4, v5, s29, v4
	s_waitcnt lgkmcnt(1)
	v_bfe_u32 v5, v20, 16, 1
	s_addc_u32 s7, s14, s7
	v_add3_u32 v5, v20, v5, s28
	s_waitcnt lgkmcnt(0)
	v_bfe_u32 v6, v22, 16, 1
	v_lshl_add_u64 v[8:9], s[6:7], 0, v[74:75]
	v_lshrrev_b32_e32 v5, 16, v5
	v_add3_u32 v6, v22, v6, s28
	v_and_or_b32 v5, v6, s29, v5
	v_lshl_add_u64 v[24:25], v[8:9], 0, v[78:79]
	global_store_dwordx4 v[24:25], v[2:5], off nt
	v_bfe_u32 v6, v23, 16, 1
	v_add3_u32 v10, v23, v6, s28
	v_bfe_u32 v2, v7, 16, 1
	v_add3_u32 v2, v7, v2, s28
	v_bfe_u32 v3, v11, 16, 1
	v_lshrrev_b32_e32 v2, 16, v2
	v_add3_u32 v3, v11, v3, s28
	v_and_or_b32 v2, v3, s29, v2
	v_bfe_u32 v3, v13, 16, 1
	v_add3_u32 v3, v13, v3, s28
	v_bfe_u32 v4, v15, 16, 1
	v_lshrrev_b32_e32 v3, 16, v3
	v_add3_u32 v4, v15, v4, s28
	v_and_or_b32 v3, v4, s29, v3
	v_bfe_u32 v4, v17, 16, 1
	v_add3_u32 v4, v17, v4, s28
	v_bfe_u32 v5, v19, 16, 1
	v_lshrrev_b32_e32 v4, 16, v4
	v_add3_u32 v5, v19, v5, s28
	v_and_or_b32 v4, v5, s29, v4
	v_bfe_u32 v5, v21, 16, 1
	v_add3_u32 v5, v21, v5, s28
	v_lshrrev_b32_e32 v5, 16, v5
	ds_read2_b32 v[6:7], v94 offset0:16 offset1:24
	v_and_or_b32 v5, v10, s29, v5
	v_lshl_add_u64 v[10:11], v[8:9], 0, v[80:81]
	global_store_dwordx4 v[10:11], v[2:5], off nt
	ds_read2_b32 v[10:11], v94 offset0:49 offset1:57
	ds_read2_b32 v[12:13], v94 offset0:82 offset1:90
	ds_read2_b32 v[14:15], v94 offset0:115 offset1:123
	s_waitcnt lgkmcnt(3)
	v_bfe_u32 v2, v6, 16, 1
	v_add3_u32 v2, v6, v2, s28
	s_waitcnt lgkmcnt(2)
	v_bfe_u32 v3, v10, 16, 1
	ds_read2_b32 v[16:17], v94 offset0:148 offset1:156
	v_lshrrev_b32_e32 v2, 16, v2
	v_add3_u32 v3, v10, v3, s28
	ds_read2_b32 v[18:19], v94 offset0:181 offset1:189
	v_and_or_b32 v2, v3, s29, v2
	s_waitcnt lgkmcnt(3)
	v_bfe_u32 v3, v12, 16, 1
	v_add3_u32 v3, v12, v3, s28
	s_waitcnt lgkmcnt(2)
	v_bfe_u32 v4, v14, 16, 1
	ds_read2_b32 v[20:21], v94 offset0:214 offset1:222
	v_lshrrev_b32_e32 v3, 16, v3
	v_add3_u32 v4, v14, v4, s28
	ds_read2_b32 v[22:23], v94 offset0:247 offset1:255
	v_and_or_b32 v3, v4, s29, v3
	s_waitcnt lgkmcnt(3)
	v_bfe_u32 v4, v16, 16, 1
	v_add3_u32 v4, v16, v4, s28
	s_waitcnt lgkmcnt(2)
	v_bfe_u32 v5, v18, 16, 1
	v_lshrrev_b32_e32 v4, 16, v4
	v_add3_u32 v5, v18, v5, s28
	v_and_or_b32 v4, v5, s29, v4
	s_waitcnt lgkmcnt(1)
	v_bfe_u32 v5, v20, 16, 1
	v_add3_u32 v5, v20, v5, s28
	s_waitcnt lgkmcnt(0)
	v_bfe_u32 v6, v22, 16, 1
	v_lshrrev_b32_e32 v5, 16, v5
	v_add3_u32 v6, v22, v6, s28
	v_and_or_b32 v5, v6, s29, v5
	v_lshl_add_u64 v[24:25], v[8:9], 0, v[82:83]
	global_store_dwordx4 v[24:25], v[2:5], off nt
	v_bfe_u32 v6, v23, 16, 1
	v_add3_u32 v6, v23, v6, s28
	v_bfe_u32 v2, v7, 16, 1
	v_add3_u32 v2, v7, v2, s28
	v_bfe_u32 v3, v11, 16, 1
	v_lshrrev_b32_e32 v2, 16, v2
	v_add3_u32 v3, v11, v3, s28
	v_and_or_b32 v2, v3, s29, v2
	v_bfe_u32 v3, v13, 16, 1
	v_add3_u32 v3, v13, v3, s28
	v_bfe_u32 v4, v15, 16, 1
	v_lshrrev_b32_e32 v3, 16, v3
	v_add3_u32 v4, v15, v4, s28
	v_and_or_b32 v3, v4, s29, v3
	v_bfe_u32 v4, v17, 16, 1
	v_add3_u32 v4, v17, v4, s28
	v_bfe_u32 v5, v19, 16, 1
	v_lshrrev_b32_e32 v4, 16, v4
	v_add3_u32 v5, v19, v5, s28
	v_and_or_b32 v4, v5, s29, v4
	v_bfe_u32 v5, v21, 16, 1
	v_add3_u32 v5, v21, v5, s28
	v_lshrrev_b32_e32 v5, 16, v5
	v_and_or_b32 v5, v6, s29, v5
	v_lshl_add_u64 v[6:7], v[8:9], 0, v[84:85]
	global_store_dwordx4 v[6:7], v[2:5], off nt
	s_waitcnt lgkmcnt(0)
	s_mov_b64 s[6:7], 0

.LBB0_545:
	v_mul_u32_u24_e32 v2, s24, v1
	v_lshlrev_b32_e32 v74, 2, v2
	v_mul_u32_u24_e32 v4, s24, v91
	v_lshl_add_u64 v[2:3], s[22:23], 0, v[74:75]
	v_lshlrev_b32_e32 v74, 2, v4
	v_mul_u32_u24_e32 v10, s24, v92
	v_lshl_add_u64 v[4:5], s[22:23], 0, v[74:75]
	v_lshlrev_b32_e32 v74, 2, v10
	v_mul_u32_u24_e32 v12, s24, v93
	v_lshl_add_u64 v[10:11], s[22:23], 0, v[74:75]
	v_lshlrev_b32_e32 v74, 2, v12
	v_mul_u32_u24_e32 v26, s24, v77
	v_lshl_add_u64 v[12:13], s[22:23], 0, v[74:75]
	v_lshlrev_b32_e32 v74, 2, v26
	v_mul_u32_u24_e32 v28, s24, v88
	v_lshl_add_u64 v[26:27], s[22:23], 0, v[74:75]
	v_lshlrev_b32_e32 v74, 2, v28
	v_mul_u32_u24_e32 v42, s24, v89
	v_lshl_add_u64 v[28:29], s[22:23], 0, v[74:75]
	v_lshlrev_b32_e32 v74, 2, v42
	v_mul_u32_u24_e32 v44, s24, v90
	v_lshl_add_u64 v[42:43], s[22:23], 0, v[74:75]
	v_lshlrev_b32_e32 v74, 2, v44
	v_mov_b32_e32 v87, v75
	v_lshl_add_u64 v[44:45], s[22:23], 0, v[74:75]
	v_lshl_add_u64 v[2:3], v[2:3], 0, v[86:87]
	v_lshl_add_u64 v[4:5], v[4:5], 0, v[86:87]
	v_lshl_add_u64 v[10:11], v[10:11], 0, v[86:87]
	v_lshl_add_u64 v[12:13], v[12:13], 0, v[86:87]
	v_lshl_add_u64 v[26:27], v[26:27], 0, v[86:87]
	v_lshl_add_u64 v[28:29], v[28:29], 0, v[86:87]
	v_lshl_add_u64 v[42:43], v[42:43], 0, v[86:87]
	v_lshl_add_u64 v[44:45], v[44:45], 0, v[86:87]
	global_load_dwordx4 v[6:9], v[2:3], off nt
	s_nop 0
	global_load_dwordx4 v[2:5], v[4:5], off nt
	s_nop 0
	global_load_dwordx4 v[14:17], v[10:11], off nt
	s_nop 0
	global_load_dwordx4 v[10:13], v[12:13], off nt
	s_nop 0
	global_load_dwordx4 v[30:33], v[26:27], off nt
	s_nop 0
	global_load_dwordx4 v[26:29], v[28:29], off nt
	s_nop 0
	global_load_dwordx4 v[46:49], v[42:43], off nt
	s_nop 0
	global_load_dwordx4 v[42:45], v[44:45], off nt
	v_add_u32_e32 v96, 0x420, v95
	v_add_u32_e32 v97, 0x428, v95
	v_add_u32_e32 v98, 0x840, v95
	v_add_u32_e32 v99, 0x848, v95
	v_add_u32_e32 v100, 0xc60, v95
	v_add_u32_e32 v101, 0xc68, v95
	v_add_u32_e32 v102, 0x1080, v95
	v_add_u32_e32 v103, 0x1088, v95
	v_add_u32_e32 v104, 0x14a0, v95
	v_add_u32_e32 v105, 0x14a8, v95
	v_add_u32_e32 v106, 0x18c0, v95
	v_add_u32_e32 v107, 0x18c8, v95
	v_add_u32_e32 v108, 0x1ce0, v95
	v_add_u32_e32 v109, 0x1ce8, v95
	s_waitcnt vmcnt(0)
	ds_write2_b32 v95, v22, v23 offset1:1
	ds_write2_b32 v95, v24, v25 offset0:2 offset1:3
	ds_write2_b32 v96, v18, v19 offset1:1
	ds_write2_b32 v97, v20, v21 offset1:1
	ds_write2_b32 v98, v38, v39 offset1:1
	ds_write2_b32 v99, v40, v41 offset1:1
	ds_write2_b32 v100, v34, v35 offset1:1
	ds_write2_b32 v101, v36, v37 offset1:1
	ds_write2_b32 v102, v54, v55 offset1:1
	ds_write2_b32 v103, v56, v57 offset1:1
	ds_write2_b32 v104, v50, v51 offset1:1
	ds_write2_b32 v105, v52, v53 offset1:1
	ds_write2_b32 v106, v62, v63 offset1:1
	ds_write2_b32 v107, v64, v65 offset1:1
	ds_write2_b32 v108, v58, v59 offset1:1
	ds_write2_b32 v109, v60, v61 offset1:1
	s_waitcnt lgkmcnt(0)
	ds_read2_b32 v[22:23], v94 offset1:8
	ds_read2_b32 v[34:35], v94 offset0:33 offset1:41
	ds_read2_b32 v[36:37], v94 offset0:66 offset1:74
	ds_read2_b32 v[38:39], v94 offset0:99 offset1:107
	ds_read2_b32 v[40:41], v94 offset0:132 offset1:140
	s_waitcnt lgkmcnt(4)
	v_bfe_u32 v18, v22, 16, 1
	v_add3_u32 v18, v22, v18, s28
	s_waitcnt lgkmcnt(3)
	v_bfe_u32 v19, v34, 16, 1
	v_lshrrev_b32_e32 v18, 16, v18
	v_add3_u32 v19, v34, v19, s28
	ds_read2_b32 v[50:51], v94 offset0:165 offset1:173
	v_and_or_b32 v18, v19, s29, v18
	s_waitcnt lgkmcnt(3)
	v_bfe_u32 v19, v36, 16, 1
	v_add3_u32 v19, v36, v19, s28
	s_waitcnt lgkmcnt(2)
	v_bfe_u32 v20, v38, 16, 1
	ds_read2_b32 v[52:53], v94 offset0:198 offset1:206
	v_lshrrev_b32_e32 v19, 16, v19
	v_add3_u32 v20, v38, v20, s28
	ds_read2_b32 v[54:55], v94 offset0:231 offset1:239
	s_lshl_b64 s[16:17], s[16:17], 12
	v_and_or_b32 v19, v20, s29, v19
	s_waitcnt lgkmcnt(3)
	v_bfe_u32 v20, v40, 16, 1
	s_add_u32 s20, s20, s16
	v_add3_u32 v20, v40, v20, s28
	s_waitcnt lgkmcnt(2)
	v_bfe_u32 v21, v50, 16, 1
	s_addc_u32 s21, s21, s17
	s_lshl_b64 s[16:17], s[0:1], 1
	v_lshrrev_b32_e32 v20, 16, v20
	v_add3_u32 v21, v50, v21, s28
	s_add_u32 s16, s20, s16
	v_and_or_b32 v20, v21, s29, v20
	s_waitcnt lgkmcnt(1)
	v_bfe_u32 v21, v52, 16, 1
	s_addc_u32 s17, s21, s17
	v_lshlrev_b32_e32 v74, 1, v76
	v_add3_u32 v21, v52, v21, s28
	s_waitcnt lgkmcnt(0)
	v_bfe_u32 v22, v54, 16, 1
	v_lshl_add_u64 v[24:25], s[16:17], 0, v[74:75]
	v_lshrrev_b32_e32 v21, 16, v21
	v_add3_u32 v22, v54, v22, s28
	v_and_or_b32 v21, v22, s29, v21
	v_lshl_add_u64 v[56:57], v[24:25], 0, v[78:79]
	global_store_dwordx4 v[56:57], v[18:21], off nt
	v_bfe_u32 v22, v55, 16, 1
	v_add3_u32 v34, v55, v22, s28
	v_bfe_u32 v18, v23, 16, 1
	v_add3_u32 v18, v23, v18, s28
	v_bfe_u32 v19, v35, 16, 1
	v_lshrrev_b32_e32 v18, 16, v18
	v_add3_u32 v19, v35, v19, s28
	v_and_or_b32 v18, v19, s29, v18
	v_bfe_u32 v19, v37, 16, 1
	v_add3_u32 v19, v37, v19, s28
	v_bfe_u32 v20, v39, 16, 1
	v_lshrrev_b32_e32 v19, 16, v19
	v_add3_u32 v20, v39, v20, s28
	v_and_or_b32 v19, v20, s29, v19
	v_bfe_u32 v20, v41, 16, 1
	v_add3_u32 v20, v41, v20, s28
	v_bfe_u32 v21, v51, 16, 1
	v_lshrrev_b32_e32 v20, 16, v20
	v_add3_u32 v21, v51, v21, s28
	v_and_or_b32 v20, v21, s29, v20
	v_bfe_u32 v21, v53, 16, 1
	v_add3_u32 v21, v53, v21, s28
	v_lshrrev_b32_e32 v21, 16, v21
	ds_read2_b32 v[22:23], v94 offset0:16 offset1:24
	v_and_or_b32 v21, v34, s29, v21
	v_lshl_add_u64 v[34:35], v[24:25], 0, v[80:81]
	global_store_dwordx4 v[34:35], v[18:21], off nt
	ds_read2_b32 v[34:35], v94 offset0:49 offset1:57
	ds_read2_b32 v[36:37], v94 offset0:82 offset1:90
	ds_read2_b32 v[38:39], v94 offset0:115 offset1:123
	s_waitcnt lgkmcnt(3)
	v_bfe_u32 v18, v22, 16, 1
	v_add3_u32 v18, v22, v18, s28
	s_waitcnt lgkmcnt(2)
	v_bfe_u32 v19, v34, 16, 1
	ds_read2_b32 v[40:41], v94 offset0:148 offset1:156
	v_lshrrev_b32_e32 v18, 16, v18
	v_add3_u32 v19, v34, v19, s28
	ds_read2_b32 v[50:51], v94 offset0:181 offset1:189
	v_and_or_b32 v18, v19, s29, v18
	s_waitcnt lgkmcnt(3)
	v_bfe_u32 v19, v36, 16, 1
	v_add3_u32 v19, v36, v19, s28
	s_waitcnt lgkmcnt(2)
	v_bfe_u32 v20, v38, 16, 1
	ds_read2_b32 v[52:53], v94 offset0:214 offset1:222
	v_lshrrev_b32_e32 v19, 16, v19
	v_add3_u32 v20, v38, v20, s28
	ds_read2_b32 v[54:55], v94 offset0:247 offset1:255
	v_and_or_b32 v19, v20, s29, v19
	s_waitcnt lgkmcnt(3)
	v_bfe_u32 v20, v40, 16, 1
	v_add3_u32 v20, v40, v20, s28
	s_waitcnt lgkmcnt(2)
	v_bfe_u32 v21, v50, 16, 1
	v_lshrrev_b32_e32 v20, 16, v20
	v_add3_u32 v21, v50, v21, s28
	v_and_or_b32 v20, v21, s29, v20
	s_waitcnt lgkmcnt(1)
	v_bfe_u32 v21, v52, 16, 1
	v_add3_u32 v21, v52, v21, s28
	s_waitcnt lgkmcnt(0)
	v_bfe_u32 v22, v54, 16, 1
	v_lshrrev_b32_e32 v21, 16, v21
	v_add3_u32 v22, v54, v22, s28
	v_and_or_b32 v21, v22, s29, v21
	v_lshl_add_u64 v[56:57], v[24:25], 0, v[82:83]
	global_store_dwordx4 v[56:57], v[18:21], off nt
	v_bfe_u32 v22, v55, 16, 1
	v_add3_u32 v22, v55, v22, s28
	v_bfe_u32 v18, v23, 16, 1
	v_add3_u32 v18, v23, v18, s28
	v_bfe_u32 v19, v35, 16, 1
	v_lshrrev_b32_e32 v18, 16, v18
	v_add3_u32 v19, v35, v19, s28
	v_and_or_b32 v18, v19, s29, v18
	v_bfe_u32 v19, v37, 16, 1
	v_add3_u32 v19, v37, v19, s28
	v_bfe_u32 v20, v39, 16, 1
	v_lshrrev_b32_e32 v19, 16, v19
	v_add3_u32 v20, v39, v20, s28
	v_and_or_b32 v19, v20, s29, v19
	v_bfe_u32 v20, v41, 16, 1
	v_add3_u32 v20, v41, v20, s28
	v_bfe_u32 v21, v51, 16, 1
	v_lshrrev_b32_e32 v20, 16, v20
	v_add3_u32 v21, v51, v21, s28
	v_and_or_b32 v20, v21, s29, v20
	v_bfe_u32 v21, v53, 16, 1
	v_add3_u32 v21, v53, v21, s28
	v_lshrrev_b32_e32 v21, 16, v21
	v_and_or_b32 v21, v22, s29, v21
	v_lshl_add_u64 v[22:23], v[24:25], 0, v[84:85]
	global_store_dwordx4 v[22:23], v[18:21], off nt
	s_waitcnt lgkmcnt(0)
	s_add_i32 s31, s30, 2
	s_cmpk_gt_u32 s30, 0x3fd
	s_mov_b64 s[26:27], -1
	s_cbranch_scc0 .LBB0_555
	s_cmpk_gt_u32 s30, 0x7fd
	s_cbranch_scc0 .LBB0_552
	s_cmpk_gt_u32 s30, 0xffd
	s_mov_b64 s[20:21], -1
	s_cbranch_scc0 .LBB0_549
	s_add_i32 s0, s31, 0xf000
	s_and_b32 s16, s0, 0xffff
	s_mul_i32 s16, s16, 0xba2f
	s_lshr_b32 s17, s16, 24
	s_mul_i32 s16, s17, 0x160
	s_sub_i32 s20, s0, s16
	s_lshl_b32 s0, s20, 5
	s_and_b32 s16, s20, 0xffff
	s_add_i32 s21, s0, 0xea00
	s_cmpk_gt_u32 s16, 0xaf
	s_cselect_b32 s0, s21, s0
	s_sext_i32_i16 s16, s0
	s_cselect_b32 s21, 0x80, 0
	s_bfe_u32 s16, s16, 0x70018
	s_add_i32 s16, s0, s16
	s_sext_i32_i16 s22, s16
	s_and_b32 s16, s16, 0xff80
	s_sub_i32 s0, s0, s16
	s_lshl_b32 s22, s22, 1
	s_sext_i32_i16 s0, s0
	s_and_b32 s22, s22, 0xffffff00
	s_add_i32 s0, s21, s0
	s_add_i32 s16, s0, s22
	s_lshl_b32 s0, s17, 6
	s_mul_i32 s17, s17, 0x2c0000
	s_add_u32 s17, s84, s17
	s_addc_u32 s21, s85, 0
	s_lshl_b32 s20, s20, 7
	s_and_b32 s20, s20, 0x3ff80
	s_add_u32 s22, s17, s20
	s_addc_u32 s23, s21, 0
	s_ashr_i32 s17, s16, 31
	s_mov_b64 s[20:21], 0

.LBB0_557:
	v_mul_u32_u24_e32 v18, s24, v1
	v_mul_u32_u24_e32 v20, s24, v91
	v_mul_u32_u24_e32 v34, s24, v92
	v_mul_u32_u24_e32 v36, s24, v93
	v_mul_u32_u24_e32 v50, s24, v77
	v_mul_u32_u24_e32 v52, s24, v88
	v_mul_u32_u24_e32 v58, s24, v89
	v_mul_u32_u24_e32 v60, s24, v90
	v_lshlrev_b32_e32 v18, 2, v18
	v_mov_b32_e32 v19, v75
	v_lshlrev_b32_e32 v20, 2, v20
	v_mov_b32_e32 v21, v75
	v_lshlrev_b32_e32 v34, 2, v34
	v_mov_b32_e32 v35, v75
	v_lshlrev_b32_e32 v36, 2, v36
	v_mov_b32_e32 v37, v75
	v_lshlrev_b32_e32 v50, 2, v50
	v_mov_b32_e32 v51, v75
	v_lshlrev_b32_e32 v52, 2, v52
	v_mov_b32_e32 v53, v75
	v_lshlrev_b32_e32 v58, 2, v58
	v_mov_b32_e32 v59, v75
	v_lshlrev_b32_e32 v60, 2, v60
	v_mov_b32_e32 v61, v75
	v_lshl_add_u64 v[18:19], s[22:23], 0, v[18:19]
	v_mov_b32_e32 v87, v75
	v_lshl_add_u64 v[20:21], s[22:23], 0, v[20:21]
	v_lshl_add_u64 v[34:35], s[22:23], 0, v[34:35]
	v_lshl_add_u64 v[36:37], s[22:23], 0, v[36:37]
	v_lshl_add_u64 v[50:51], s[22:23], 0, v[50:51]
	v_lshl_add_u64 v[52:53], s[22:23], 0, v[52:53]
	v_lshl_add_u64 v[58:59], s[22:23], 0, v[58:59]
	v_lshl_add_u64 v[60:61], s[22:23], 0, v[60:61]
	v_lshl_add_u64 v[18:19], v[18:19], 0, v[86:87]
	v_lshl_add_u64 v[20:21], v[20:21], 0, v[86:87]
	v_lshl_add_u64 v[34:35], v[34:35], 0, v[86:87]
	v_lshl_add_u64 v[36:37], v[36:37], 0, v[86:87]
	v_lshl_add_u64 v[50:51], v[50:51], 0, v[86:87]
	v_lshl_add_u64 v[52:53], v[52:53], 0, v[86:87]
	v_lshl_add_u64 v[58:59], v[58:59], 0, v[86:87]
	v_lshl_add_u64 v[60:61], v[60:61], 0, v[86:87]
	global_load_dwordx4 v[22:25], v[18:19], off nt
	s_nop 0
	global_load_dwordx4 v[18:21], v[20:21], off nt
	s_nop 0
	global_load_dwordx4 v[38:41], v[34:35], off nt
	s_nop 0
	global_load_dwordx4 v[34:37], v[36:37], off nt
	s_nop 0
	global_load_dwordx4 v[54:57], v[50:51], off nt
	s_nop 0
	global_load_dwordx4 v[50:53], v[52:53], off nt
	s_nop 0
	global_load_dwordx4 v[66:69], v[58:59], off nt
	s_nop 0
	global_load_dwordx4 v[58:61], v[60:61], off nt
	ds_write2_b32 v95, v6, v7 offset1:1
	ds_write2_b32 v95, v8, v9 offset0:2 offset1:3
	ds_write2_b32 v96, v2, v3 offset1:1
	ds_write2_b32 v97, v4, v5 offset1:1
	ds_write2_b32 v98, v14, v15 offset1:1
	ds_write2_b32 v99, v16, v17 offset1:1
	ds_write2_b32 v100, v10, v11 offset1:1
	ds_write2_b32 v101, v12, v13 offset1:1
	ds_write2_b32 v102, v30, v31 offset1:1
	ds_write2_b32 v103, v32, v33 offset1:1
	ds_write2_b32 v104, v26, v27 offset1:1
	ds_write2_b32 v105, v28, v29 offset1:1
	ds_write2_b32 v106, v46, v47 offset1:1
	ds_write2_b32 v107, v48, v49 offset1:1
	ds_write2_b32 v108, v42, v43 offset1:1
	ds_write2_b32 v109, v44, v45 offset1:1
	s_waitcnt lgkmcnt(0)
	ds_read2_b32 v[6:7], v94 offset1:8
	ds_read2_b32 v[10:11], v94 offset0:33 offset1:41
	ds_read2_b32 v[12:13], v94 offset0:66 offset1:74
	ds_read2_b32 v[14:15], v94 offset0:99 offset1:107
	ds_read2_b32 v[16:17], v94 offset0:132 offset1:140
	s_waitcnt lgkmcnt(4)
	v_bfe_u32 v2, v6, 16, 1
	v_add3_u32 v2, v6, v2, s28
	s_waitcnt lgkmcnt(3)
	v_bfe_u32 v3, v10, 16, 1
	v_lshrrev_b32_e32 v2, 16, v2
	v_add3_u32 v3, v10, v3, s28
	ds_read2_b32 v[26:27], v94 offset0:165 offset1:173
	v_and_or_b32 v2, v3, s29, v2
	s_waitcnt lgkmcnt(3)
	v_bfe_u32 v3, v12, 16, 1
	v_add3_u32 v3, v12, v3, s28
	s_waitcnt lgkmcnt(2)
	v_bfe_u32 v4, v14, 16, 1
	ds_read2_b32 v[28:29], v94 offset0:198 offset1:206
	v_lshrrev_b32_e32 v3, 16, v3
	v_add3_u32 v4, v14, v4, s28
	ds_read2_b32 v[30:31], v94 offset0:231 offset1:239
	s_lshl_b64 s[14:15], s[14:15], 12
	v_and_or_b32 v3, v4, s29, v3
	s_waitcnt lgkmcnt(3)
	v_bfe_u32 v4, v16, 16, 1
	s_add_u32 s14, s18, s14
	v_add3_u32 v4, v16, v4, s28
	s_waitcnt lgkmcnt(2)
	v_bfe_u32 v5, v26, 16, 1
	s_addc_u32 s15, s19, s15
	s_lshl_b64 s[6:7], s[6:7], 1
	v_lshrrev_b32_e32 v4, 16, v4
	v_add3_u32 v5, v26, v5, s28
	s_add_u32 s6, s14, s6
	v_and_or_b32 v4, v5, s29, v4
	s_waitcnt lgkmcnt(1)
	v_bfe_u32 v5, v28, 16, 1
	s_addc_u32 s7, s15, s7
	v_add3_u32 v5, v28, v5, s28
	s_waitcnt lgkmcnt(0)
	v_bfe_u32 v6, v30, 16, 1
	v_lshl_add_u64 v[8:9], s[6:7], 0, v[74:75]
	v_lshrrev_b32_e32 v5, 16, v5
	v_add3_u32 v6, v30, v6, s28
	v_and_or_b32 v5, v6, s29, v5
	v_lshl_add_u64 v[32:33], v[8:9], 0, v[78:79]
	global_store_dwordx4 v[32:33], v[2:5], off nt
	v_bfe_u32 v6, v31, 16, 1
	v_add3_u32 v10, v31, v6, s28
	v_bfe_u32 v2, v7, 16, 1
	v_add3_u32 v2, v7, v2, s28
	v_bfe_u32 v3, v11, 16, 1
	v_lshrrev_b32_e32 v2, 16, v2
	v_add3_u32 v3, v11, v3, s28
	v_and_or_b32 v2, v3, s29, v2
	v_bfe_u32 v3, v13, 16, 1
	v_add3_u32 v3, v13, v3, s28
	v_bfe_u32 v4, v15, 16, 1
	v_lshrrev_b32_e32 v3, 16, v3
	v_add3_u32 v4, v15, v4, s28
	v_and_or_b32 v3, v4, s29, v3
	v_bfe_u32 v4, v17, 16, 1
	v_add3_u32 v4, v17, v4, s28
	v_bfe_u32 v5, v27, 16, 1
	v_lshrrev_b32_e32 v4, 16, v4
	v_add3_u32 v5, v27, v5, s28
	v_and_or_b32 v4, v5, s29, v4
	v_bfe_u32 v5, v29, 16, 1
	v_add3_u32 v5, v29, v5, s28
	v_lshrrev_b32_e32 v5, 16, v5
	ds_read2_b32 v[6:7], v94 offset0:16 offset1:24
	v_and_or_b32 v5, v10, s29, v5
	v_lshl_add_u64 v[10:11], v[8:9], 0, v[80:81]
	global_store_dwordx4 v[10:11], v[2:5], off nt
	ds_read2_b32 v[10:11], v94 offset0:49 offset1:57
	ds_read2_b32 v[12:13], v94 offset0:82 offset1:90
	ds_read2_b32 v[14:15], v94 offset0:115 offset1:123
	s_waitcnt lgkmcnt(3)
	v_bfe_u32 v2, v6, 16, 1
	v_add3_u32 v2, v6, v2, s28
	s_waitcnt lgkmcnt(2)
	v_bfe_u32 v3, v10, 16, 1
	ds_read2_b32 v[16:17], v94 offset0:148 offset1:156
	v_lshrrev_b32_e32 v2, 16, v2
	v_add3_u32 v3, v10, v3, s28
	ds_read2_b32 v[26:27], v94 offset0:181 offset1:189
	v_and_or_b32 v2, v3, s29, v2
	s_waitcnt lgkmcnt(3)
	v_bfe_u32 v3, v12, 16, 1
	v_add3_u32 v3, v12, v3, s28
	s_waitcnt lgkmcnt(2)
	v_bfe_u32 v4, v14, 16, 1
	ds_read2_b32 v[28:29], v94 offset0:214 offset1:222
	v_lshrrev_b32_e32 v3, 16, v3
	v_add3_u32 v4, v14, v4, s28
	ds_read2_b32 v[30:31], v94 offset0:247 offset1:255
	v_and_or_b32 v3, v4, s29, v3
	s_waitcnt lgkmcnt(3)
	v_bfe_u32 v4, v16, 16, 1
	v_add3_u32 v4, v16, v4, s28
	s_waitcnt lgkmcnt(2)
	v_bfe_u32 v5, v26, 16, 1
	v_lshrrev_b32_e32 v4, 16, v4
	v_add3_u32 v5, v26, v5, s28
	v_and_or_b32 v4, v5, s29, v4
	s_waitcnt lgkmcnt(1)
	v_bfe_u32 v5, v28, 16, 1
	v_add3_u32 v5, v28, v5, s28
	s_waitcnt lgkmcnt(0)
	v_bfe_u32 v6, v30, 16, 1
	v_lshrrev_b32_e32 v5, 16, v5
	v_add3_u32 v6, v30, v6, s28
	v_and_or_b32 v5, v6, s29, v5
	v_lshl_add_u64 v[32:33], v[8:9], 0, v[82:83]
	global_store_dwordx4 v[32:33], v[2:5], off nt
	v_bfe_u32 v6, v31, 16, 1
	v_add3_u32 v6, v31, v6, s28
	v_bfe_u32 v2, v7, 16, 1
	v_add3_u32 v2, v7, v2, s28
	v_bfe_u32 v3, v11, 16, 1
	v_lshrrev_b32_e32 v2, 16, v2
	v_add3_u32 v3, v11, v3, s28
	v_and_or_b32 v2, v3, s29, v2
	v_bfe_u32 v3, v13, 16, 1
	v_add3_u32 v3, v13, v3, s28
	v_bfe_u32 v4, v15, 16, 1
	v_lshrrev_b32_e32 v3, 16, v3
	v_add3_u32 v4, v15, v4, s28
	v_and_or_b32 v3, v4, s29, v3
	v_bfe_u32 v4, v17, 16, 1
	v_add3_u32 v4, v17, v4, s28
	v_bfe_u32 v5, v27, 16, 1
	v_lshrrev_b32_e32 v4, 16, v4
	v_add3_u32 v5, v27, v5, s28
	v_and_or_b32 v4, v5, s29, v4
	v_bfe_u32 v5, v29, 16, 1
	v_add3_u32 v5, v29, v5, s28
	v_lshrrev_b32_e32 v5, 16, v5
	v_and_or_b32 v5, v6, s29, v5
	v_lshl_add_u64 v[6:7], v[8:9], 0, v[84:85]
	global_store_dwordx4 v[6:7], v[2:5], off nt
	s_waitcnt lgkmcnt(0)
	s_add_i32 s31, s30, 3
	s_cmpk_lt_u32 s30, 0x3fd
	s_mov_b64 s[26:27], -1
	s_cbranch_scc1 .LBB0_567
	s_cmpk_lt_u32 s30, 0x7fd
	s_cbranch_scc1 .LBB0_564
	s_cmpk_lt_u32 s30, 0xffd
	s_mov_b64 s[18:19], -1
	s_cbranch_scc1 .LBB0_561
	s_add_i32 s6, s31, 0xf000
	s_and_b32 s7, s6, 0xffff
	s_mul_i32 s7, s7, 0xba2f
	s_lshr_b32 s15, s7, 24
	s_mul_i32 s7, s15, 0x160
	s_sub_i32 s18, s6, s7
	s_lshl_b32 s6, s18, 5
	s_and_b32 s7, s18, 0xffff
	s_add_i32 s14, s6, 0xea00
	s_cmpk_gt_u32 s7, 0xaf
	s_cselect_b32 s6, s14, s6
	s_sext_i32_i16 s7, s6
	s_cselect_b32 s14, 0x80, 0
	s_bfe_u32 s7, s7, 0x70018
	s_add_i32 s7, s6, s7
	s_sext_i32_i16 s19, s7
	s_and_b32 s7, s7, 0xff80
	s_sub_i32 s6, s6, s7
	s_lshl_b32 s19, s19, 1
	s_sext_i32_i16 s6, s6
	s_and_b32 s19, s19, 0xffffff00
	s_add_i32 s6, s14, s6
	s_add_i32 s14, s6, s19
	s_lshl_b32 s6, s15, 6
	s_mul_i32 s15, s15, 0x2c0000
	s_add_u32 s15, s84, s15
	s_addc_u32 s19, s85, 0
	s_lshl_b32 s18, s18, 7
	s_and_b32 s18, s18, 0x3ff80
	s_add_u32 s22, s15, s18
	s_mov_b32 s7, s1
	s_addc_u32 s23, s19, 0
	s_ashr_i32 s15, s14, 31
	s_mov_b64 s[18:19], 0

.LBB0_569:
	v_mul_u32_u24_e32 v2, s24, v1
	v_mul_u32_u24_e32 v4, s24, v91
	v_mul_u32_u24_e32 v6, s24, v92
	v_lshlrev_b32_e32 v2, 2, v2
	v_mov_b32_e32 v3, v75
	v_lshlrev_b32_e32 v4, 2, v4
	v_mov_b32_e32 v5, v75
	v_lshlrev_b32_e32 v6, 2, v6
	v_mov_b32_e32 v7, v75
	v_mul_u32_u24_e32 v8, s24, v93
	v_lshl_add_u64 v[2:3], s[22:23], 0, v[2:3]
	v_mov_b32_e32 v87, v75
	v_lshl_add_u64 v[4:5], s[22:23], 0, v[4:5]
	v_lshl_add_u64 v[6:7], s[22:23], 0, v[6:7]
	v_lshlrev_b32_e32 v8, 2, v8
	v_mov_b32_e32 v9, v75
	v_lshl_add_u64 v[2:3], v[2:3], 0, v[86:87]
	v_lshl_add_u64 v[4:5], v[4:5], 0, v[86:87]
	v_lshl_add_u64 v[6:7], v[6:7], 0, v[86:87]
	v_lshl_add_u64 v[8:9], s[22:23], 0, v[8:9]
	global_load_dwordx4 v[10:13], v[2:3], off nt
	s_nop 0
	global_load_dwordx4 v[2:5], v[4:5], off nt
	v_lshl_add_u64 v[8:9], v[8:9], 0, v[86:87]
	global_load_dwordx4 v[30:33], v[6:7], off nt
	global_load_dwordx4 v[26:29], v[8:9], off nt
	v_mul_u32_u24_e32 v6, s24, v77
	v_lshlrev_b32_e32 v6, 2, v6
	v_mov_b32_e32 v7, v75
	v_mul_u32_u24_e32 v8, s24, v88
	v_lshl_add_u64 v[6:7], s[22:23], 0, v[6:7]
	v_lshlrev_b32_e32 v8, 2, v8
	v_mov_b32_e32 v9, v75
	v_lshl_add_u64 v[6:7], v[6:7], 0, v[86:87]
	v_lshl_add_u64 v[8:9], s[22:23], 0, v[8:9]
	v_lshl_add_u64 v[8:9], v[8:9], 0, v[86:87]
	global_load_dwordx4 v[46:49], v[6:7], off nt
	global_load_dwordx4 v[42:45], v[8:9], off nt
	v_mul_u32_u24_e32 v6, s24, v89
	v_lshlrev_b32_e32 v6, 2, v6
	v_mov_b32_e32 v7, v75
	v_mul_u32_u24_e32 v8, s24, v90
	v_lshl_add_u64 v[6:7], s[22:23], 0, v[6:7]
	v_lshlrev_b32_e32 v8, 2, v8
	v_mov_b32_e32 v9, v75
	v_lshl_add_u64 v[6:7], v[6:7], 0, v[86:87]
	v_lshl_add_u64 v[8:9], s[22:23], 0, v[8:9]
	v_lshl_add_u64 v[8:9], v[8:9], 0, v[86:87]
	global_load_dwordx4 v[70:73], v[6:7], off nt
	global_load_dwordx4 v[62:65], v[8:9], off nt
	s_waitcnt vmcnt(19)
	ds_write2_b32 v95, v22, v23 offset1:1
	ds_write2_b32 v95, v24, v25 offset0:2 offset1:3
	s_waitcnt vmcnt(18)
	ds_write2_b32 v96, v18, v19 offset1:1
	ds_write2_b32 v97, v20, v21 offset1:1
	s_waitcnt vmcnt(17)
	ds_write2_b32 v98, v38, v39 offset1:1
	ds_write2_b32 v99, v40, v41 offset1:1
	s_waitcnt vmcnt(16)
	ds_write2_b32 v100, v34, v35 offset1:1
	ds_write2_b32 v101, v36, v37 offset1:1
	s_waitcnt vmcnt(15)
	ds_write2_b32 v102, v54, v55 offset1:1
	ds_write2_b32 v103, v56, v57 offset1:1
	s_waitcnt vmcnt(14)
	ds_write2_b32 v104, v50, v51 offset1:1
	ds_write2_b32 v105, v52, v53 offset1:1
	s_waitcnt vmcnt(13)
	ds_write2_b32 v106, v66, v67 offset1:1
	ds_write2_b32 v107, v68, v69 offset1:1
	s_waitcnt vmcnt(12)
	ds_write2_b32 v108, v58, v59 offset1:1
	ds_write2_b32 v109, v60, v61 offset1:1
	s_waitcnt lgkmcnt(0)
	ds_read2_b32 v[14:15], v94 offset1:8
	ds_read2_b32 v[18:19], v94 offset0:33 offset1:41
	ds_read2_b32 v[20:21], v94 offset0:66 offset1:74
	ds_read2_b32 v[22:23], v94 offset0:99 offset1:107
	ds_read2_b32 v[24:25], v94 offset0:132 offset1:140
	s_waitcnt lgkmcnt(4)
	v_bfe_u32 v6, v14, 16, 1
	v_add3_u32 v6, v14, v6, s28
	s_waitcnt lgkmcnt(3)
	v_bfe_u32 v7, v18, 16, 1
	v_lshrrev_b32_e32 v6, 16, v6
	v_add3_u32 v7, v18, v7, s28
	ds_read2_b32 v[34:35], v94 offset0:165 offset1:173
	v_and_or_b32 v6, v7, s29, v6
	s_waitcnt lgkmcnt(3)
	v_bfe_u32 v7, v20, 16, 1
	v_add3_u32 v7, v20, v7, s28
	s_waitcnt lgkmcnt(2)
	v_bfe_u32 v8, v22, 16, 1
	ds_read2_b32 v[36:37], v94 offset0:198 offset1:206
	v_lshrrev_b32_e32 v7, 16, v7
	v_add3_u32 v8, v22, v8, s28
	ds_read2_b32 v[38:39], v94 offset0:231 offset1:239
	s_lshl_b64 s[16:17], s[16:17], 12
	v_and_or_b32 v7, v8, s29, v7
	s_waitcnt lgkmcnt(3)
	v_bfe_u32 v8, v24, 16, 1
	s_add_u32 s20, s20, s16
	v_add3_u32 v8, v24, v8, s28
	s_waitcnt lgkmcnt(2)
	v_bfe_u32 v9, v34, 16, 1
	s_addc_u32 s21, s21, s17
	s_lshl_b64 s[16:17], s[0:1], 1
	v_lshrrev_b32_e32 v8, 16, v8
	v_add3_u32 v9, v34, v9, s28
	s_add_u32 s16, s20, s16
	v_and_or_b32 v8, v9, s29, v8
	s_waitcnt lgkmcnt(1)
	v_bfe_u32 v9, v36, 16, 1
	s_addc_u32 s17, s21, s17
	v_add3_u32 v9, v36, v9, s28
	s_waitcnt lgkmcnt(0)
	v_bfe_u32 v14, v38, 16, 1
	v_lshl_add_u64 v[16:17], s[16:17], 0, v[74:75]
	v_lshrrev_b32_e32 v9, 16, v9
	v_add3_u32 v14, v38, v14, s28
	v_and_or_b32 v9, v14, s29, v9
	v_lshl_add_u64 v[40:41], v[16:17], 0, v[78:79]
	global_store_dwordx4 v[40:41], v[6:9], off nt
	v_bfe_u32 v14, v39, 16, 1
	v_add3_u32 v18, v39, v14, s28
	v_bfe_u32 v6, v15, 16, 1
	v_add3_u32 v6, v15, v6, s28
	v_bfe_u32 v7, v19, 16, 1
	v_lshrrev_b32_e32 v6, 16, v6
	v_add3_u32 v7, v19, v7, s28
	v_and_or_b32 v6, v7, s29, v6
	v_bfe_u32 v7, v21, 16, 1
	v_add3_u32 v7, v21, v7, s28
	v_bfe_u32 v8, v23, 16, 1
	v_lshrrev_b32_e32 v7, 16, v7
	v_add3_u32 v8, v23, v8, s28
	v_and_or_b32 v7, v8, s29, v7
	v_bfe_u32 v8, v25, 16, 1
	v_add3_u32 v8, v25, v8, s28
	v_bfe_u32 v9, v35, 16, 1
	v_lshrrev_b32_e32 v8, 16, v8
	v_add3_u32 v9, v35, v9, s28
	v_and_or_b32 v8, v9, s29, v8
	v_bfe_u32 v9, v37, 16, 1
	v_add3_u32 v9, v37, v9, s28
	v_lshrrev_b32_e32 v9, 16, v9
	ds_read2_b32 v[14:15], v94 offset0:16 offset1:24
	v_and_or_b32 v9, v18, s29, v9
	v_lshl_add_u64 v[18:19], v[16:17], 0, v[80:81]
	global_store_dwordx4 v[18:19], v[6:9], off nt
	ds_read2_b32 v[18:19], v94 offset0:49 offset1:57
	ds_read2_b32 v[20:21], v94 offset0:82 offset1:90
	ds_read2_b32 v[22:23], v94 offset0:115 offset1:123
	s_waitcnt lgkmcnt(3)
	v_bfe_u32 v6, v14, 16, 1
	v_add3_u32 v6, v14, v6, s28
	s_waitcnt lgkmcnt(2)
	v_bfe_u32 v7, v18, 16, 1
	ds_read2_b32 v[24:25], v94 offset0:148 offset1:156
	v_lshrrev_b32_e32 v6, 16, v6
	v_add3_u32 v7, v18, v7, s28
	ds_read2_b32 v[34:35], v94 offset0:181 offset1:189
	v_and_or_b32 v6, v7, s29, v6
	s_waitcnt lgkmcnt(3)
	v_bfe_u32 v7, v20, 16, 1
	v_add3_u32 v7, v20, v7, s28
	s_waitcnt lgkmcnt(2)
	v_bfe_u32 v8, v22, 16, 1
	ds_read2_b32 v[36:37], v94 offset0:214 offset1:222
	v_lshrrev_b32_e32 v7, 16, v7
	v_add3_u32 v8, v22, v8, s28
	ds_read2_b32 v[38:39], v94 offset0:247 offset1:255
	v_and_or_b32 v7, v8, s29, v7
	s_waitcnt lgkmcnt(3)
	v_bfe_u32 v8, v24, 16, 1
	v_add3_u32 v8, v24, v8, s28
	s_waitcnt lgkmcnt(2)
	v_bfe_u32 v9, v34, 16, 1
	v_lshrrev_b32_e32 v8, 16, v8
	v_add3_u32 v9, v34, v9, s28
	v_and_or_b32 v8, v9, s29, v8
	s_waitcnt lgkmcnt(1)
	v_bfe_u32 v9, v36, 16, 1
	v_add3_u32 v9, v36, v9, s28
	s_waitcnt lgkmcnt(0)
	v_bfe_u32 v14, v38, 16, 1
	v_lshrrev_b32_e32 v9, 16, v9
	v_add3_u32 v14, v38, v14, s28
	v_and_or_b32 v9, v14, s29, v9
	v_lshl_add_u64 v[40:41], v[16:17], 0, v[82:83]
	global_store_dwordx4 v[40:41], v[6:9], off nt
	v_bfe_u32 v14, v39, 16, 1
	v_add3_u32 v14, v39, v14, s28
	v_bfe_u32 v6, v15, 16, 1
	v_add3_u32 v6, v15, v6, s28
	v_bfe_u32 v7, v19, 16, 1
	v_lshrrev_b32_e32 v6, 16, v6
	v_add3_u32 v7, v19, v7, s28
	v_and_or_b32 v6, v7, s29, v6
	v_bfe_u32 v7, v21, 16, 1
	v_add3_u32 v7, v21, v7, s28
	v_bfe_u32 v8, v23, 16, 1
	v_lshrrev_b32_e32 v7, 16, v7
	v_add3_u32 v8, v23, v8, s28
	v_and_or_b32 v7, v8, s29, v7
	v_bfe_u32 v8, v25, 16, 1
	v_add3_u32 v8, v25, v8, s28
	v_bfe_u32 v9, v35, 16, 1
	v_lshrrev_b32_e32 v8, 16, v8
	v_add3_u32 v9, v35, v9, s28
	v_and_or_b32 v8, v9, s29, v8
	v_bfe_u32 v9, v37, 16, 1
	v_add3_u32 v9, v37, v9, s28
	v_lshrrev_b32_e32 v9, 16, v9
	v_and_or_b32 v9, v14, s29, v9
	v_lshl_add_u64 v[14:15], v[16:17], 0, v[84:85]
	global_store_dwordx4 v[14:15], v[6:9], off nt
	s_waitcnt lgkmcnt(0)
	s_add_i32 s31, s30, 4
	s_cmpk_lt_u32 s30, 0x3fc
	s_mov_b64 s[26:27], -1
	s_cbranch_scc1 .LBB0_579
	s_cmpk_lt_u32 s30, 0x7fc
	s_cbranch_scc1 .LBB0_576
	s_cmpk_lt_u32 s30, 0xffc
	s_mov_b64 s[20:21], -1
	s_cbranch_scc1 .LBB0_573
	s_add_i32 s0, s31, 0xf000
	s_and_b32 s16, s0, 0xffff
	s_mul_i32 s16, s16, 0xba2f
	s_lshr_b32 s17, s16, 24
	s_mul_i32 s16, s17, 0x160
	s_sub_i32 s20, s0, s16
	s_lshl_b32 s0, s20, 5
	s_and_b32 s16, s20, 0xffff
	s_add_i32 s21, s0, 0xea00
	s_cmpk_gt_u32 s16, 0xaf
	s_cselect_b32 s0, s21, s0
	s_sext_i32_i16 s16, s0
	s_cselect_b32 s21, 0x80, 0
	s_bfe_u32 s16, s16, 0x70018
	s_add_i32 s16, s0, s16
	s_sext_i32_i16 s22, s16
	s_and_b32 s16, s16, 0xff80
	s_sub_i32 s0, s0, s16
	s_lshl_b32 s22, s22, 1
	s_sext_i32_i16 s0, s0
	s_and_b32 s22, s22, 0xffffff00
	s_add_i32 s0, s21, s0
	s_add_i32 s16, s0, s22
	s_lshl_b32 s0, s17, 6
	s_mul_i32 s17, s17, 0x2c0000
	s_add_u32 s17, s84, s17
	s_addc_u32 s21, s85, 0
	s_lshl_b32 s20, s20, 7
	s_and_b32 s20, s20, 0x3ff80
	s_add_u32 s22, s17, s20
	s_addc_u32 s23, s21, 0
	s_ashr_i32 s17, s16, 31
	s_mov_b64 s[20:21], 0

.LBB0_581:
	v_mul_u32_u24_e32 v6, s24, v1
	v_mul_u32_u24_e32 v8, s24, v91
	v_mul_u32_u24_e32 v18, s24, v92
	v_mul_u32_u24_e32 v20, s24, v93
	v_mul_u32_u24_e32 v22, s24, v77
	v_lshlrev_b32_e32 v6, 2, v6
	v_mov_b32_e32 v7, v75
	v_lshlrev_b32_e32 v8, 2, v8
	v_mov_b32_e32 v9, v75
	v_lshlrev_b32_e32 v18, 2, v18
	v_mov_b32_e32 v19, v75
	v_lshlrev_b32_e32 v20, 2, v20
	v_mov_b32_e32 v21, v75
	v_lshlrev_b32_e32 v22, 2, v22
	v_mov_b32_e32 v23, v75
	v_mul_u32_u24_e32 v24, s24, v88
	v_lshl_add_u64 v[6:7], s[22:23], 0, v[6:7]
	v_mov_b32_e32 v87, v75
	v_lshl_add_u64 v[8:9], s[22:23], 0, v[8:9]
	v_lshl_add_u64 v[18:19], s[22:23], 0, v[18:19]
	v_lshl_add_u64 v[20:21], s[22:23], 0, v[20:21]
	v_lshl_add_u64 v[22:23], s[22:23], 0, v[22:23]
	v_lshlrev_b32_e32 v24, 2, v24
	v_mov_b32_e32 v25, v75
	v_lshl_add_u64 v[6:7], v[6:7], 0, v[86:87]
	v_lshl_add_u64 v[8:9], v[8:9], 0, v[86:87]
	v_lshl_add_u64 v[18:19], v[18:19], 0, v[86:87]
	v_lshl_add_u64 v[20:21], v[20:21], 0, v[86:87]
	v_lshl_add_u64 v[22:23], v[22:23], 0, v[86:87]
	v_lshl_add_u64 v[24:25], s[22:23], 0, v[24:25]
	global_load_dwordx4 v[14:17], v[6:7], off nt
	s_nop 0
	global_load_dwordx4 v[6:9], v[8:9], off nt
	s_nop 0
	global_load_dwordx4 v[34:37], v[18:19], off nt
	s_nop 0
	global_load_dwordx4 v[18:21], v[20:21], off nt
	v_lshl_add_u64 v[24:25], v[24:25], 0, v[86:87]
	global_load_dwordx4 v[50:53], v[22:23], off nt
	global_load_dwordx4 v[38:41], v[24:25], off nt
	v_mul_u32_u24_e32 v22, s24, v89
	v_lshlrev_b32_e32 v22, 2, v22
	v_mov_b32_e32 v23, v75
	v_mul_u32_u24_e32 v24, s24, v90
	v_lshl_add_u64 v[22:23], s[22:23], 0, v[22:23]
	v_lshlrev_b32_e32 v24, 2, v24
	v_mov_b32_e32 v25, v75
	v_lshl_add_u64 v[22:23], v[22:23], 0, v[86:87]
	v_lshl_add_u64 v[24:25], s[22:23], 0, v[24:25]
	v_lshl_add_u64 v[24:25], v[24:25], 0, v[86:87]
	global_load_dwordx4 v[66:69], v[22:23], off nt
	global_load_dwordx4 v[54:57], v[24:25], off nt
	s_waitcnt vmcnt(19)
	ds_write2_b32 v95, v10, v11 offset1:1
	ds_write2_b32 v95, v12, v13 offset0:2 offset1:3
	s_waitcnt vmcnt(18)
	ds_write2_b32 v96, v2, v3 offset1:1
	ds_write2_b32 v97, v4, v5 offset1:1
	s_waitcnt vmcnt(17)
	ds_write2_b32 v98, v30, v31 offset1:1
	ds_write2_b32 v99, v32, v33 offset1:1
	s_waitcnt vmcnt(16)
	ds_write2_b32 v100, v26, v27 offset1:1
	ds_write2_b32 v101, v28, v29 offset1:1
	s_waitcnt vmcnt(15)
	ds_write2_b32 v102, v46, v47 offset1:1
	ds_write2_b32 v103, v48, v49 offset1:1
	s_waitcnt vmcnt(14)
	ds_write2_b32 v104, v42, v43 offset1:1
	ds_write2_b32 v105, v44, v45 offset1:1
	s_waitcnt vmcnt(13)
	ds_write2_b32 v106, v70, v71 offset1:1
	ds_write2_b32 v107, v72, v73 offset1:1
	s_waitcnt vmcnt(12)
	ds_write2_b32 v108, v62, v63 offset1:1
	ds_write2_b32 v109, v64, v65 offset1:1
	s_waitcnt lgkmcnt(0)
	ds_read2_b32 v[10:11], v94 offset1:8
	ds_read2_b32 v[22:23], v94 offset0:33 offset1:41
	ds_read2_b32 v[24:25], v94 offset0:66 offset1:74
	ds_read2_b32 v[26:27], v94 offset0:99 offset1:107
	ds_read2_b32 v[28:29], v94 offset0:132 offset1:140
	s_waitcnt lgkmcnt(4)
	v_bfe_u32 v2, v10, 16, 1
	v_add3_u32 v2, v10, v2, s28
	s_waitcnt lgkmcnt(3)
	v_bfe_u32 v3, v22, 16, 1
	v_lshrrev_b32_e32 v2, 16, v2
	v_add3_u32 v3, v22, v3, s28
	ds_read2_b32 v[30:31], v94 offset0:165 offset1:173
	v_and_or_b32 v2, v3, s29, v2
	s_waitcnt lgkmcnt(3)
	v_bfe_u32 v3, v24, 16, 1
	v_add3_u32 v3, v24, v3, s28
	s_waitcnt lgkmcnt(2)
	v_bfe_u32 v4, v26, 16, 1
	ds_read2_b32 v[32:33], v94 offset0:198 offset1:206
	v_lshrrev_b32_e32 v3, 16, v3
	v_add3_u32 v4, v26, v4, s28
	ds_read2_b32 v[42:43], v94 offset0:231 offset1:239
	s_lshl_b64 s[14:15], s[14:15], 12
	v_and_or_b32 v3, v4, s29, v3
	s_waitcnt lgkmcnt(3)
	v_bfe_u32 v4, v28, 16, 1
	s_add_u32 s14, s18, s14
	v_add3_u32 v4, v28, v4, s28
	s_waitcnt lgkmcnt(2)
	v_bfe_u32 v5, v30, 16, 1
	s_addc_u32 s15, s19, s15
	s_lshl_b64 s[6:7], s[6:7], 1
	v_lshrrev_b32_e32 v4, 16, v4
	v_add3_u32 v5, v30, v5, s28
	s_add_u32 s6, s14, s6
	v_and_or_b32 v4, v5, s29, v4
	s_waitcnt lgkmcnt(1)
	v_bfe_u32 v5, v32, 16, 1
	s_addc_u32 s7, s15, s7
	v_add3_u32 v5, v32, v5, s28
	s_waitcnt lgkmcnt(0)
	v_bfe_u32 v10, v42, 16, 1
	v_lshl_add_u64 v[12:13], s[6:7], 0, v[74:75]
	v_lshrrev_b32_e32 v5, 16, v5
	v_add3_u32 v10, v42, v10, s28
	v_and_or_b32 v5, v10, s29, v5
	v_lshl_add_u64 v[44:45], v[12:13], 0, v[78:79]
	global_store_dwordx4 v[44:45], v[2:5], off nt
	v_bfe_u32 v10, v43, 16, 1
	v_add3_u32 v22, v43, v10, s28
	v_bfe_u32 v2, v11, 16, 1
	v_add3_u32 v2, v11, v2, s28
	v_bfe_u32 v3, v23, 16, 1
	v_lshrrev_b32_e32 v2, 16, v2
	v_add3_u32 v3, v23, v3, s28
	v_and_or_b32 v2, v3, s29, v2
	v_bfe_u32 v3, v25, 16, 1
	v_add3_u32 v3, v25, v3, s28
	v_bfe_u32 v4, v27, 16, 1
	v_lshrrev_b32_e32 v3, 16, v3
	v_add3_u32 v4, v27, v4, s28
	v_and_or_b32 v3, v4, s29, v3
	v_bfe_u32 v4, v29, 16, 1
	v_add3_u32 v4, v29, v4, s28
	v_bfe_u32 v5, v31, 16, 1
	v_lshrrev_b32_e32 v4, 16, v4
	v_add3_u32 v5, v31, v5, s28
	v_and_or_b32 v4, v5, s29, v4
	v_bfe_u32 v5, v33, 16, 1
	v_add3_u32 v5, v33, v5, s28
	v_lshrrev_b32_e32 v5, 16, v5
	ds_read2_b32 v[10:11], v94 offset0:16 offset1:24
	v_and_or_b32 v5, v22, s29, v5
	v_lshl_add_u64 v[22:23], v[12:13], 0, v[80:81]
	global_store_dwordx4 v[22:23], v[2:5], off nt
	ds_read2_b32 v[22:23], v94 offset0:49 offset1:57
	ds_read2_b32 v[24:25], v94 offset0:82 offset1:90
	ds_read2_b32 v[26:27], v94 offset0:115 offset1:123
	s_waitcnt lgkmcnt(3)
	v_bfe_u32 v2, v10, 16, 1
	v_add3_u32 v2, v10, v2, s28
	s_waitcnt lgkmcnt(2)
	v_bfe_u32 v3, v22, 16, 1
	ds_read2_b32 v[28:29], v94 offset0:148 offset1:156
	v_lshrrev_b32_e32 v2, 16, v2
	v_add3_u32 v3, v22, v3, s28
	ds_read2_b32 v[30:31], v94 offset0:181 offset1:189
	v_and_or_b32 v2, v3, s29, v2
	s_waitcnt lgkmcnt(3)
	v_bfe_u32 v3, v24, 16, 1
	v_add3_u32 v3, v24, v3, s28
	s_waitcnt lgkmcnt(2)
	v_bfe_u32 v4, v26, 16, 1
	ds_read2_b32 v[32:33], v94 offset0:214 offset1:222
	v_lshrrev_b32_e32 v3, 16, v3
	v_add3_u32 v4, v26, v4, s28
	ds_read2_b32 v[42:43], v94 offset0:247 offset1:255
	v_and_or_b32 v3, v4, s29, v3
	s_waitcnt lgkmcnt(3)
	v_bfe_u32 v4, v28, 16, 1
	v_add3_u32 v4, v28, v4, s28
	s_waitcnt lgkmcnt(2)
	v_bfe_u32 v5, v30, 16, 1
	v_lshrrev_b32_e32 v4, 16, v4
	v_add3_u32 v5, v30, v5, s28
	v_and_or_b32 v4, v5, s29, v4
	s_waitcnt lgkmcnt(1)
	v_bfe_u32 v5, v32, 16, 1
	v_add3_u32 v5, v32, v5, s28
	s_waitcnt lgkmcnt(0)
	v_bfe_u32 v10, v42, 16, 1
	v_lshrrev_b32_e32 v5, 16, v5
	v_add3_u32 v10, v42, v10, s28
	v_and_or_b32 v5, v10, s29, v5
	v_lshl_add_u64 v[44:45], v[12:13], 0, v[82:83]
	global_store_dwordx4 v[44:45], v[2:5], off nt
	v_bfe_u32 v10, v43, 16, 1
	v_add3_u32 v10, v43, v10, s28
	v_bfe_u32 v2, v11, 16, 1
	v_add3_u32 v2, v11, v2, s28
	v_bfe_u32 v3, v23, 16, 1
	v_lshrrev_b32_e32 v2, 16, v2
	v_add3_u32 v3, v23, v3, s28
	v_and_or_b32 v2, v3, s29, v2
	v_bfe_u32 v3, v25, 16, 1
	v_add3_u32 v3, v25, v3, s28
	v_bfe_u32 v4, v27, 16, 1
	v_lshrrev_b32_e32 v3, 16, v3
	v_add3_u32 v4, v27, v4, s28
	v_and_or_b32 v3, v4, s29, v3
	v_bfe_u32 v4, v29, 16, 1
	v_add3_u32 v4, v29, v4, s28
	v_bfe_u32 v5, v31, 16, 1
	v_lshrrev_b32_e32 v4, 16, v4
	v_add3_u32 v5, v31, v5, s28
	v_and_or_b32 v4, v5, s29, v4
	v_bfe_u32 v5, v33, 16, 1
	v_add3_u32 v5, v33, v5, s28
	v_lshrrev_b32_e32 v5, 16, v5
	v_and_or_b32 v5, v10, s29, v5
	v_lshl_add_u64 v[10:11], v[12:13], 0, v[84:85]
	global_store_dwordx4 v[10:11], v[2:5], off nt
	s_waitcnt lgkmcnt(0)
	s_add_i32 s31, s30, 5
	s_cmpk_lt_u32 s30, 0x3fb
	s_mov_b64 s[26:27], -1
	s_cbranch_scc1 .LBB0_591
	s_cmpk_lt_u32 s30, 0x7fb
	s_cbranch_scc1 .LBB0_588
	s_cmpk_lt_u32 s30, 0xffb
	s_mov_b64 s[18:19], -1
	s_cbranch_scc1 .LBB0_585
	s_add_i32 s6, s31, 0xf000
	s_and_b32 s7, s6, 0xffff
	s_mul_i32 s7, s7, 0xba2f
	s_lshr_b32 s15, s7, 24
	s_mul_i32 s7, s15, 0x160
	s_sub_i32 s18, s6, s7
	s_lshl_b32 s6, s18, 5
	s_and_b32 s7, s18, 0xffff
	s_add_i32 s14, s6, 0xea00
	s_cmpk_gt_u32 s7, 0xaf
	s_cselect_b32 s6, s14, s6
	s_sext_i32_i16 s7, s6
	s_cselect_b32 s14, 0x80, 0
	s_bfe_u32 s7, s7, 0x70018
	s_add_i32 s7, s6, s7
	s_sext_i32_i16 s19, s7
	s_and_b32 s7, s7, 0xff80
	s_sub_i32 s6, s6, s7
	s_lshl_b32 s19, s19, 1
	s_sext_i32_i16 s6, s6
	s_and_b32 s19, s19, 0xffffff00
	s_add_i32 s6, s14, s6
	s_add_i32 s14, s6, s19
	s_lshl_b32 s6, s15, 6
	s_mul_i32 s15, s15, 0x2c0000
	s_add_u32 s15, s84, s15
	s_addc_u32 s19, s85, 0
	s_lshl_b32 s18, s18, 7
	s_and_b32 s18, s18, 0x3ff80
	s_add_u32 s22, s15, s18
	s_mov_b32 s7, s1
	s_addc_u32 s23, s19, 0
	s_ashr_i32 s15, s14, 31
	s_mov_b64 s[18:19], 0

.LBB0_593:
	v_mul_u32_u24_e32 v2, s24, v1
	v_mul_u32_u24_e32 v4, s24, v91
	v_mul_u32_u24_e32 v22, s24, v92
	v_mul_u32_u24_e32 v24, s24, v93
	v_mul_u32_u24_e32 v30, s24, v77
	v_lshlrev_b32_e32 v2, 2, v2
	v_mov_b32_e32 v3, v75
	v_lshlrev_b32_e32 v4, 2, v4
	v_mov_b32_e32 v5, v75
	v_lshlrev_b32_e32 v22, 2, v22
	v_mov_b32_e32 v23, v75
	v_lshlrev_b32_e32 v24, 2, v24
	v_mov_b32_e32 v25, v75
	v_lshlrev_b32_e32 v30, 2, v30
	v_mov_b32_e32 v31, v75
	v_mul_u32_u24_e32 v32, s24, v88
	v_lshl_add_u64 v[2:3], s[22:23], 0, v[2:3]
	v_mov_b32_e32 v87, v75
	v_lshl_add_u64 v[4:5], s[22:23], 0, v[4:5]
	v_lshl_add_u64 v[22:23], s[22:23], 0, v[22:23]
	v_lshl_add_u64 v[24:25], s[22:23], 0, v[24:25]
	v_lshl_add_u64 v[30:31], s[22:23], 0, v[30:31]
	v_lshlrev_b32_e32 v32, 2, v32
	v_mov_b32_e32 v33, v75
	v_lshl_add_u64 v[2:3], v[2:3], 0, v[86:87]
	v_lshl_add_u64 v[4:5], v[4:5], 0, v[86:87]
	v_lshl_add_u64 v[22:23], v[22:23], 0, v[86:87]
	v_lshl_add_u64 v[24:25], v[24:25], 0, v[86:87]
	v_lshl_add_u64 v[30:31], v[30:31], 0, v[86:87]
	v_lshl_add_u64 v[32:33], s[22:23], 0, v[32:33]
	global_load_dwordx4 v[10:13], v[2:3], off nt
	s_nop 0
	global_load_dwordx4 v[2:5], v[4:5], off nt
	s_nop 0
	global_load_dwordx4 v[26:29], v[22:23], off nt
	s_nop 0
	global_load_dwordx4 v[22:25], v[24:25], off nt
	v_lshl_add_u64 v[32:33], v[32:33], 0, v[86:87]
	global_load_dwordx4 v[46:49], v[30:31], off nt
	global_load_dwordx4 v[42:45], v[32:33], off nt
	v_mul_u32_u24_e32 v30, s24, v89
	v_lshlrev_b32_e32 v30, 2, v30
	v_mov_b32_e32 v31, v75
	v_mul_u32_u24_e32 v32, s24, v90
	v_lshl_add_u64 v[30:31], s[22:23], 0, v[30:31]
	v_lshlrev_b32_e32 v32, 2, v32
	v_mov_b32_e32 v33, v75
	v_lshl_add_u64 v[30:31], v[30:31], 0, v[86:87]
	v_lshl_add_u64 v[32:33], s[22:23], 0, v[32:33]
	v_lshl_add_u64 v[32:33], v[32:33], 0, v[86:87]
	global_load_dwordx4 v[62:65], v[30:31], off nt
	global_load_dwordx4 v[58:61], v[32:33], off nt
	s_waitcnt vmcnt(19)
	ds_write2_b32 v95, v14, v15 offset1:1
	ds_write2_b32 v95, v16, v17 offset0:2 offset1:3
	s_waitcnt vmcnt(18)
	ds_write2_b32 v96, v6, v7 offset1:1
	ds_write2_b32 v97, v8, v9 offset1:1
	s_waitcnt vmcnt(17)
	ds_write2_b32 v98, v34, v35 offset1:1
	ds_write2_b32 v99, v36, v37 offset1:1
	s_waitcnt vmcnt(16)
	ds_write2_b32 v100, v18, v19 offset1:1
	ds_write2_b32 v101, v20, v21 offset1:1
	s_waitcnt vmcnt(15)
	ds_write2_b32 v102, v50, v51 offset1:1
	ds_write2_b32 v103, v52, v53 offset1:1
	s_waitcnt vmcnt(14)
	ds_write2_b32 v104, v38, v39 offset1:1
	ds_write2_b32 v105, v40, v41 offset1:1
	s_waitcnt vmcnt(13)
	ds_write2_b32 v106, v66, v67 offset1:1
	ds_write2_b32 v107, v68, v69 offset1:1
	s_waitcnt vmcnt(12)
	ds_write2_b32 v108, v54, v55 offset1:1
	ds_write2_b32 v109, v56, v57 offset1:1
	s_waitcnt lgkmcnt(0)
	ds_read2_b32 v[14:15], v94 offset1:8
	ds_read2_b32 v[18:19], v94 offset0:33 offset1:41
	ds_read2_b32 v[20:21], v94 offset0:66 offset1:74
	ds_read2_b32 v[30:31], v94 offset0:99 offset1:107
	ds_read2_b32 v[32:33], v94 offset0:132 offset1:140
	s_waitcnt lgkmcnt(4)
	v_bfe_u32 v6, v14, 16, 1
	v_add3_u32 v6, v14, v6, s28
	s_waitcnt lgkmcnt(3)
	v_bfe_u32 v7, v18, 16, 1
	v_lshrrev_b32_e32 v6, 16, v6
	v_add3_u32 v7, v18, v7, s28
	ds_read2_b32 v[34:35], v94 offset0:165 offset1:173
	v_and_or_b32 v6, v7, s29, v6
	s_waitcnt lgkmcnt(3)
	v_bfe_u32 v7, v20, 16, 1
	v_add3_u32 v7, v20, v7, s28
	s_waitcnt lgkmcnt(2)
	v_bfe_u32 v8, v30, 16, 1
	ds_read2_b32 v[36:37], v94 offset0:198 offset1:206
	v_lshrrev_b32_e32 v7, 16, v7
	v_add3_u32 v8, v30, v8, s28
	ds_read2_b32 v[38:39], v94 offset0:231 offset1:239
	s_lshl_b64 s[16:17], s[16:17], 12
	v_and_or_b32 v7, v8, s29, v7
	s_waitcnt lgkmcnt(3)
	v_bfe_u32 v8, v32, 16, 1
	s_add_u32 s20, s20, s16
	v_add3_u32 v8, v32, v8, s28
	s_waitcnt lgkmcnt(2)
	v_bfe_u32 v9, v34, 16, 1
	s_addc_u32 s21, s21, s17
	s_lshl_b64 s[16:17], s[0:1], 1
	v_lshrrev_b32_e32 v8, 16, v8
	v_add3_u32 v9, v34, v9, s28
	s_add_u32 s16, s20, s16
	v_and_or_b32 v8, v9, s29, v8
	s_waitcnt lgkmcnt(1)
	v_bfe_u32 v9, v36, 16, 1
	s_addc_u32 s17, s21, s17
	v_add3_u32 v9, v36, v9, s28
	s_waitcnt lgkmcnt(0)
	v_bfe_u32 v14, v38, 16, 1
	v_lshl_add_u64 v[16:17], s[16:17], 0, v[74:75]
	v_lshrrev_b32_e32 v9, 16, v9
	v_add3_u32 v14, v38, v14, s28
	v_and_or_b32 v9, v14, s29, v9
	v_lshl_add_u64 v[40:41], v[16:17], 0, v[78:79]
	global_store_dwordx4 v[40:41], v[6:9], off nt
	v_bfe_u32 v14, v39, 16, 1
	v_add3_u32 v18, v39, v14, s28
	v_bfe_u32 v6, v15, 16, 1
	v_add3_u32 v6, v15, v6, s28
	v_bfe_u32 v7, v19, 16, 1
	v_lshrrev_b32_e32 v6, 16, v6
	v_add3_u32 v7, v19, v7, s28
	v_and_or_b32 v6, v7, s29, v6
	v_bfe_u32 v7, v21, 16, 1
	v_add3_u32 v7, v21, v7, s28
	v_bfe_u32 v8, v31, 16, 1
	v_lshrrev_b32_e32 v7, 16, v7
	v_add3_u32 v8, v31, v8, s28
	v_and_or_b32 v7, v8, s29, v7
	v_bfe_u32 v8, v33, 16, 1
	v_add3_u32 v8, v33, v8, s28
	v_bfe_u32 v9, v35, 16, 1
	v_lshrrev_b32_e32 v8, 16, v8
	v_add3_u32 v9, v35, v9, s28
	v_and_or_b32 v8, v9, s29, v8
	v_bfe_u32 v9, v37, 16, 1
	v_add3_u32 v9, v37, v9, s28
	v_lshrrev_b32_e32 v9, 16, v9
	ds_read2_b32 v[14:15], v94 offset0:16 offset1:24
	v_and_or_b32 v9, v18, s29, v9
	v_lshl_add_u64 v[18:19], v[16:17], 0, v[80:81]
	global_store_dwordx4 v[18:19], v[6:9], off nt
	ds_read2_b32 v[18:19], v94 offset0:49 offset1:57
	ds_read2_b32 v[20:21], v94 offset0:82 offset1:90
	ds_read2_b32 v[30:31], v94 offset0:115 offset1:123
	s_waitcnt lgkmcnt(3)
	v_bfe_u32 v6, v14, 16, 1
	v_add3_u32 v6, v14, v6, s28
	s_waitcnt lgkmcnt(2)
	v_bfe_u32 v7, v18, 16, 1
	ds_read2_b32 v[32:33], v94 offset0:148 offset1:156
	v_lshrrev_b32_e32 v6, 16, v6
	v_add3_u32 v7, v18, v7, s28
	ds_read2_b32 v[34:35], v94 offset0:181 offset1:189
	v_and_or_b32 v6, v7, s29, v6
	s_waitcnt lgkmcnt(3)
	v_bfe_u32 v7, v20, 16, 1
	v_add3_u32 v7, v20, v7, s28
	s_waitcnt lgkmcnt(2)
	v_bfe_u32 v8, v30, 16, 1
	ds_read2_b32 v[36:37], v94 offset0:214 offset1:222
	v_lshrrev_b32_e32 v7, 16, v7
	v_add3_u32 v8, v30, v8, s28
	ds_read2_b32 v[38:39], v94 offset0:247 offset1:255
	v_and_or_b32 v7, v8, s29, v7
	s_waitcnt lgkmcnt(3)
	v_bfe_u32 v8, v32, 16, 1
	v_add3_u32 v8, v32, v8, s28
	s_waitcnt lgkmcnt(2)
	v_bfe_u32 v9, v34, 16, 1
	v_lshrrev_b32_e32 v8, 16, v8
	v_add3_u32 v9, v34, v9, s28
	v_and_or_b32 v8, v9, s29, v8
	s_waitcnt lgkmcnt(1)
	v_bfe_u32 v9, v36, 16, 1
	v_add3_u32 v9, v36, v9, s28
	s_waitcnt lgkmcnt(0)
	v_bfe_u32 v14, v38, 16, 1
	v_lshrrev_b32_e32 v9, 16, v9
	v_add3_u32 v14, v38, v14, s28
	v_and_or_b32 v9, v14, s29, v9
	v_lshl_add_u64 v[40:41], v[16:17], 0, v[82:83]
	global_store_dwordx4 v[40:41], v[6:9], off nt
	v_bfe_u32 v14, v39, 16, 1
	v_add3_u32 v14, v39, v14, s28
	v_bfe_u32 v6, v15, 16, 1
	v_add3_u32 v6, v15, v6, s28
	v_bfe_u32 v7, v19, 16, 1
	v_lshrrev_b32_e32 v6, 16, v6
	v_add3_u32 v7, v19, v7, s28
	v_and_or_b32 v6, v7, s29, v6
	v_bfe_u32 v7, v21, 16, 1
	v_add3_u32 v7, v21, v7, s28
	v_bfe_u32 v8, v31, 16, 1
	v_lshrrev_b32_e32 v7, 16, v7
	v_add3_u32 v8, v31, v8, s28
	v_and_or_b32 v7, v8, s29, v7
	v_bfe_u32 v8, v33, 16, 1
	v_add3_u32 v8, v33, v8, s28
	v_bfe_u32 v9, v35, 16, 1
	v_lshrrev_b32_e32 v8, 16, v8
	v_add3_u32 v9, v35, v9, s28
	v_and_or_b32 v8, v9, s29, v8
	v_bfe_u32 v9, v37, 16, 1
	v_add3_u32 v9, v37, v9, s28
	v_lshrrev_b32_e32 v9, 16, v9
	v_and_or_b32 v9, v14, s29, v9
	v_lshl_add_u64 v[14:15], v[16:17], 0, v[84:85]
	global_store_dwordx4 v[14:15], v[6:9], off nt
	s_waitcnt lgkmcnt(0)
	s_add_i32 s31, s30, 6
	s_cmpk_lt_u32 s30, 0x3fa
	s_mov_b64 s[26:27], -1
	s_cbranch_scc1 .LBB0_603
	s_cmpk_lt_u32 s30, 0x7fa
	s_cbranch_scc1 .LBB0_600
	s_cmpk_lt_u32 s30, 0xffa
	s_mov_b64 s[20:21], -1
	s_cbranch_scc1 .LBB0_597
	s_add_i32 s0, s31, 0xf000
	s_and_b32 s16, s0, 0xffff
	s_mul_i32 s16, s16, 0xba2f
	s_lshr_b32 s17, s16, 24
	s_mul_i32 s16, s17, 0x160
	s_sub_i32 s20, s0, s16
	s_lshl_b32 s0, s20, 5
	s_and_b32 s16, s20, 0xffff
	s_add_i32 s21, s0, 0xea00
	s_cmpk_gt_u32 s16, 0xaf
	s_cselect_b32 s0, s21, s0
	s_sext_i32_i16 s16, s0
	s_cselect_b32 s21, 0x80, 0
	s_bfe_u32 s16, s16, 0x70018
	s_add_i32 s16, s0, s16
	s_sext_i32_i16 s22, s16
	s_and_b32 s16, s16, 0xff80
	s_sub_i32 s0, s0, s16
	s_lshl_b32 s22, s22, 1
	s_sext_i32_i16 s0, s0
	s_and_b32 s22, s22, 0xffffff00
	s_add_i32 s0, s21, s0
	s_add_i32 s16, s0, s22
	s_lshl_b32 s0, s17, 6
	s_mul_i32 s17, s17, 0x2c0000
	s_add_u32 s17, s84, s17
	s_addc_u32 s21, s85, 0
	s_lshl_b32 s20, s20, 7
	s_and_b32 s20, s20, 0x3ff80
	s_add_u32 s22, s17, s20
	s_addc_u32 s23, s21, 0
	s_ashr_i32 s17, s16, 31
	s_mov_b64 s[20:21], 0

.LBB0_605:
	v_mul_u32_u24_e32 v6, s24, v1
	v_mul_u32_u24_e32 v8, s24, v91
	v_mul_u32_u24_e32 v18, s24, v92
	v_mul_u32_u24_e32 v20, s24, v93
	v_mul_u32_u24_e32 v34, s24, v77
	v_mul_u32_u24_e32 v36, s24, v88
	v_mul_u32_u24_e32 v50, s24, v89
	v_mul_u32_u24_e32 v52, s24, v90
	v_lshlrev_b32_e32 v6, 2, v6
	v_mov_b32_e32 v7, v75
	v_lshlrev_b32_e32 v8, 2, v8
	v_mov_b32_e32 v9, v75
	v_lshlrev_b32_e32 v18, 2, v18
	v_mov_b32_e32 v19, v75
	v_lshlrev_b32_e32 v20, 2, v20
	v_mov_b32_e32 v21, v75
	v_lshlrev_b32_e32 v34, 2, v34
	v_mov_b32_e32 v35, v75
	v_lshlrev_b32_e32 v36, 2, v36
	v_mov_b32_e32 v37, v75
	v_lshlrev_b32_e32 v50, 2, v50
	v_mov_b32_e32 v51, v75
	v_lshlrev_b32_e32 v52, 2, v52
	v_mov_b32_e32 v53, v75
	v_lshl_add_u64 v[6:7], s[22:23], 0, v[6:7]
	v_mov_b32_e32 v87, v75
	v_lshl_add_u64 v[8:9], s[22:23], 0, v[8:9]
	v_lshl_add_u64 v[18:19], s[22:23], 0, v[18:19]
	v_lshl_add_u64 v[20:21], s[22:23], 0, v[20:21]
	v_lshl_add_u64 v[34:35], s[22:23], 0, v[34:35]
	v_lshl_add_u64 v[36:37], s[22:23], 0, v[36:37]
	v_lshl_add_u64 v[50:51], s[22:23], 0, v[50:51]
	v_lshl_add_u64 v[52:53], s[22:23], 0, v[52:53]
	v_lshl_add_u64 v[6:7], v[6:7], 0, v[86:87]
	v_lshl_add_u64 v[8:9], v[8:9], 0, v[86:87]
	v_lshl_add_u64 v[18:19], v[18:19], 0, v[86:87]
	v_lshl_add_u64 v[20:21], v[20:21], 0, v[86:87]
	v_lshl_add_u64 v[34:35], v[34:35], 0, v[86:87]
	v_lshl_add_u64 v[36:37], v[36:37], 0, v[86:87]
	v_lshl_add_u64 v[50:51], v[50:51], 0, v[86:87]
	v_lshl_add_u64 v[52:53], v[52:53], 0, v[86:87]
	global_load_dwordx4 v[14:17], v[6:7], off nt
	s_nop 0
	global_load_dwordx4 v[6:9], v[8:9], off nt
	s_nop 0
	global_load_dwordx4 v[30:33], v[18:19], off nt
	s_nop 0
	global_load_dwordx4 v[18:21], v[20:21], off nt
	s_nop 0
	global_load_dwordx4 v[38:41], v[34:35], off nt
	s_nop 0
	global_load_dwordx4 v[34:37], v[36:37], off nt
	s_nop 0
	global_load_dwordx4 v[54:57], v[50:51], off nt
	s_nop 0
	global_load_dwordx4 v[50:53], v[52:53], off nt
	s_waitcnt vmcnt(19)
	ds_write2_b32 v95, v10, v11 offset1:1
	ds_write2_b32 v95, v12, v13 offset0:2 offset1:3
	s_waitcnt vmcnt(18)
	ds_write2_b32 v96, v2, v3 offset1:1
	ds_write2_b32 v97, v4, v5 offset1:1
	s_waitcnt vmcnt(17)
	ds_write2_b32 v98, v26, v27 offset1:1
	ds_write2_b32 v99, v28, v29 offset1:1
	s_waitcnt vmcnt(16)
	ds_write2_b32 v100, v22, v23 offset1:1
	ds_write2_b32 v101, v24, v25 offset1:1
	s_waitcnt vmcnt(15)
	ds_write2_b32 v102, v46, v47 offset1:1
	ds_write2_b32 v103, v48, v49 offset1:1
	s_waitcnt vmcnt(14)
	ds_write2_b32 v104, v42, v43 offset1:1
	ds_write2_b32 v105, v44, v45 offset1:1
	s_waitcnt vmcnt(13)
	ds_write2_b32 v106, v62, v63 offset1:1
	ds_write2_b32 v107, v64, v65 offset1:1
	s_waitcnt vmcnt(12)
	ds_write2_b32 v108, v58, v59 offset1:1
	ds_write2_b32 v109, v60, v61 offset1:1
	s_waitcnt lgkmcnt(0)
	ds_read2_b32 v[10:11], v94 offset1:8
	ds_read2_b32 v[22:23], v94 offset0:33 offset1:41
	ds_read2_b32 v[24:25], v94 offset0:66 offset1:74
	ds_read2_b32 v[26:27], v94 offset0:99 offset1:107
	ds_read2_b32 v[28:29], v94 offset0:132 offset1:140
	s_waitcnt lgkmcnt(4)
	v_bfe_u32 v2, v10, 16, 1
	v_add3_u32 v2, v10, v2, s28
	s_waitcnt lgkmcnt(3)
	v_bfe_u32 v3, v22, 16, 1
	v_lshrrev_b32_e32 v2, 16, v2
	v_add3_u32 v3, v22, v3, s28
	ds_read2_b32 v[42:43], v94 offset0:165 offset1:173
	v_and_or_b32 v2, v3, s29, v2
	s_waitcnt lgkmcnt(3)
	v_bfe_u32 v3, v24, 16, 1
	v_add3_u32 v3, v24, v3, s28
	s_waitcnt lgkmcnt(2)
	v_bfe_u32 v4, v26, 16, 1
	ds_read2_b32 v[44:45], v94 offset0:198 offset1:206
	v_lshrrev_b32_e32 v3, 16, v3
	v_add3_u32 v4, v26, v4, s28
	ds_read2_b32 v[46:47], v94 offset0:231 offset1:239
	s_lshl_b64 s[14:15], s[14:15], 12
	v_and_or_b32 v3, v4, s29, v3
	s_waitcnt lgkmcnt(3)
	v_bfe_u32 v4, v28, 16, 1
	s_add_u32 s14, s18, s14
	v_add3_u32 v4, v28, v4, s28
	s_waitcnt lgkmcnt(2)
	v_bfe_u32 v5, v42, 16, 1
	s_addc_u32 s15, s19, s15
	s_lshl_b64 s[6:7], s[6:7], 1
	v_lshrrev_b32_e32 v4, 16, v4
	v_add3_u32 v5, v42, v5, s28
	s_add_u32 s6, s14, s6
	v_and_or_b32 v4, v5, s29, v4
	s_waitcnt lgkmcnt(1)
	v_bfe_u32 v5, v44, 16, 1
	s_addc_u32 s7, s15, s7
	v_add3_u32 v5, v44, v5, s28
	s_waitcnt lgkmcnt(0)
	v_bfe_u32 v10, v46, 16, 1
	v_lshl_add_u64 v[12:13], s[6:7], 0, v[74:75]
	v_lshrrev_b32_e32 v5, 16, v5
	v_add3_u32 v10, v46, v10, s28
	v_and_or_b32 v5, v10, s29, v5
	v_lshl_add_u64 v[48:49], v[12:13], 0, v[78:79]
	global_store_dwordx4 v[48:49], v[2:5], off nt
	v_bfe_u32 v10, v47, 16, 1
	v_add3_u32 v22, v47, v10, s28
	v_bfe_u32 v2, v11, 16, 1
	v_add3_u32 v2, v11, v2, s28
	v_bfe_u32 v3, v23, 16, 1
	v_lshrrev_b32_e32 v2, 16, v2
	v_add3_u32 v3, v23, v3, s28
	v_and_or_b32 v2, v3, s29, v2
	v_bfe_u32 v3, v25, 16, 1
	v_add3_u32 v3, v25, v3, s28
	v_bfe_u32 v4, v27, 16, 1
	v_lshrrev_b32_e32 v3, 16, v3
	v_add3_u32 v4, v27, v4, s28
	v_and_or_b32 v3, v4, s29, v3
	v_bfe_u32 v4, v29, 16, 1
	v_add3_u32 v4, v29, v4, s28
	v_bfe_u32 v5, v43, 16, 1
	v_lshrrev_b32_e32 v4, 16, v4
	v_add3_u32 v5, v43, v5, s28
	v_and_or_b32 v4, v5, s29, v4
	v_bfe_u32 v5, v45, 16, 1
	v_add3_u32 v5, v45, v5, s28
	v_lshrrev_b32_e32 v5, 16, v5
	ds_read2_b32 v[10:11], v94 offset0:16 offset1:24
	v_and_or_b32 v5, v22, s29, v5
	v_lshl_add_u64 v[22:23], v[12:13], 0, v[80:81]
	global_store_dwordx4 v[22:23], v[2:5], off nt
	ds_read2_b32 v[22:23], v94 offset0:49 offset1:57
	ds_read2_b32 v[24:25], v94 offset0:82 offset1:90
	ds_read2_b32 v[26:27], v94 offset0:115 offset1:123
	s_waitcnt lgkmcnt(3)
	v_bfe_u32 v2, v10, 16, 1
	v_add3_u32 v2, v10, v2, s28
	s_waitcnt lgkmcnt(2)
	v_bfe_u32 v3, v22, 16, 1
	ds_read2_b32 v[28:29], v94 offset0:148 offset1:156
	v_lshrrev_b32_e32 v2, 16, v2
	v_add3_u32 v3, v22, v3, s28
	ds_read2_b32 v[42:43], v94 offset0:181 offset1:189
	v_and_or_b32 v2, v3, s29, v2
	s_waitcnt lgkmcnt(3)
	v_bfe_u32 v3, v24, 16, 1
	v_add3_u32 v3, v24, v3, s28
	s_waitcnt lgkmcnt(2)
	v_bfe_u32 v4, v26, 16, 1
	ds_read2_b32 v[44:45], v94 offset0:214 offset1:222
	v_lshrrev_b32_e32 v3, 16, v3
	v_add3_u32 v4, v26, v4, s28
	ds_read2_b32 v[46:47], v94 offset0:247 offset1:255
	v_and_or_b32 v3, v4, s29, v3
	s_waitcnt lgkmcnt(3)
	v_bfe_u32 v4, v28, 16, 1
	v_add3_u32 v4, v28, v4, s28
	s_waitcnt lgkmcnt(2)
	v_bfe_u32 v5, v42, 16, 1
	v_lshrrev_b32_e32 v4, 16, v4
	v_add3_u32 v5, v42, v5, s28
	v_and_or_b32 v4, v5, s29, v4
	s_waitcnt lgkmcnt(1)
	v_bfe_u32 v5, v44, 16, 1
	v_add3_u32 v5, v44, v5, s28
	s_waitcnt lgkmcnt(0)
	v_bfe_u32 v10, v46, 16, 1
	v_lshrrev_b32_e32 v5, 16, v5
	v_add3_u32 v10, v46, v10, s28
	v_and_or_b32 v5, v10, s29, v5
	v_lshl_add_u64 v[48:49], v[12:13], 0, v[82:83]
	global_store_dwordx4 v[48:49], v[2:5], off nt
	v_bfe_u32 v10, v47, 16, 1
	v_add3_u32 v10, v47, v10, s28
	v_bfe_u32 v2, v11, 16, 1
	v_add3_u32 v2, v11, v2, s28
	v_bfe_u32 v3, v23, 16, 1
	v_lshrrev_b32_e32 v2, 16, v2
	v_add3_u32 v3, v23, v3, s28
	v_and_or_b32 v2, v3, s29, v2
	v_bfe_u32 v3, v25, 16, 1
	v_add3_u32 v3, v25, v3, s28
	v_bfe_u32 v4, v27, 16, 1
	v_lshrrev_b32_e32 v3, 16, v3
	v_add3_u32 v4, v27, v4, s28
	v_and_or_b32 v3, v4, s29, v3
	v_bfe_u32 v4, v29, 16, 1
	v_add3_u32 v4, v29, v4, s28
	v_bfe_u32 v5, v43, 16, 1
	v_lshrrev_b32_e32 v4, 16, v4
	v_add3_u32 v5, v43, v5, s28
	v_and_or_b32 v4, v5, s29, v4
	v_bfe_u32 v5, v45, 16, 1
	v_add3_u32 v5, v45, v5, s28
	v_lshrrev_b32_e32 v5, 16, v5
	v_and_or_b32 v5, v10, s29, v5
	v_lshl_add_u64 v[10:11], v[12:13], 0, v[84:85]
	global_store_dwordx4 v[10:11], v[2:5], off nt
	s_waitcnt lgkmcnt(0)
	s_add_i32 s31, s30, 7
	s_cmpk_lt_u32 s30, 0x3f9
	s_mov_b64 s[26:27], -1
	s_cbranch_scc1 .LBB0_615
	s_cmpk_lt_u32 s30, 0x7f9
	s_cbranch_scc1 .LBB0_612
	s_cmpk_lt_u32 s30, 0xff9
	s_mov_b64 s[18:19], -1
	s_cbranch_scc1 .LBB0_609
	s_add_i32 s6, s31, 0xf000
	s_and_b32 s7, s6, 0xffff
	s_mul_i32 s7, s7, 0xba2f
	s_lshr_b32 s15, s7, 24
	s_mul_i32 s7, s15, 0x160
	s_sub_i32 s18, s6, s7
	s_lshl_b32 s6, s18, 5
	s_and_b32 s7, s18, 0xffff
	s_add_i32 s14, s6, 0xea00
	s_cmpk_gt_u32 s7, 0xaf
	s_cselect_b32 s6, s14, s6
	s_sext_i32_i16 s7, s6
	s_cselect_b32 s14, 0x80, 0
	s_bfe_u32 s7, s7, 0x70018
	s_add_i32 s7, s6, s7
	s_sext_i32_i16 s19, s7
	s_and_b32 s7, s7, 0xff80
	s_sub_i32 s6, s6, s7
	s_lshl_b32 s19, s19, 1
	s_sext_i32_i16 s6, s6
	s_and_b32 s19, s19, 0xffffff00
	s_add_i32 s6, s14, s6
	s_add_i32 s14, s6, s19
	s_lshl_b32 s6, s15, 6
	s_mul_i32 s15, s15, 0x2c0000
	s_add_u32 s15, s84, s15
	s_addc_u32 s19, s85, 0
	s_lshl_b32 s18, s18, 7
	s_and_b32 s18, s18, 0x3ff80
	s_add_u32 s22, s15, s18
	s_mov_b32 s7, s1
	s_addc_u32 s23, s19, 0
	s_ashr_i32 s15, s14, 31
	s_mov_b64 s[18:19], 0

.LBB0_1295:
	s_waitcnt vmcnt(0)
	v_and_b32_e32 v129, 0xffff0000, v97
	v_and_b32_e32 v127, 0xffff0000, v96
	v_lshlrev_b32_e32 v128, 16, v97
	v_mul_f32_e32 v2, v129, v129
	v_lshlrev_b32_e32 v126, 16, v96
	v_and_b32_e32 v113, 0xffff0000, v95
	v_and_b32_e32 v112, 0xffff0000, v94
	v_pk_fma_f32 v[122:123], v[128:129], v[128:129], v[2:3] op_sel_hi:[1,1,0]
	v_mul_f32_e32 v2, v127, v127
	v_lshlrev_b32_e32 v111, 16, v95
	v_lshlrev_b32_e32 v110, 16, v94
	v_lshlrev_b32_e32 v103, 16, v88
	v_pk_mul_f32 v[124:125], v[112:113], v[112:113]
	v_pk_fma_f32 v[130:131], v[126:127], v[126:127], v[2:3] op_sel_hi:[1,1,0]
	v_and_b32_e32 v101, 0xffff0000, v88
	v_pk_fma_f32 v[124:125], v[110:111], v[110:111], v[124:125]
	v_mov_b32_e32 v102, v130
	v_mov_b32_e32 v132, v122
	v_mov_b32_e32 v133, v103
	v_and_b32_e32 v107, 0xffff0000, v92
	v_lshlrev_b32_e32 v104, 16, v89
	v_and_b32_e32 v105, 0xffff0000, v89
	v_lshlrev_b32_e32 v88, 16, v82
	v_and_b32_e32 v89, 0xffff0000, v82
	v_mul_f32_e32 v82, v101, v101
	v_pk_add_f32 v[122:123], v[130:131], v[122:123]
	v_pk_mul_f32 v[130:131], v[102:103], v[132:133]
	v_pk_add_f32 v[124:125], v[124:125], v[124:125] op_sel:[0,1] op_sel_hi:[1,0]
	v_lshlrev_b32_e32 v106, 16, v92
	v_and_b32_e32 v109, 0xffff0000, v93
	v_mov_b32_e32 v123, v131
	v_mov_b32_e32 v125, v82
	v_mul_f32_e32 v2, v107, v107
	v_lshlrev_b32_e32 v108, 16, v93
	v_pk_add_f32 v[122:123], v[122:123], v[124:125]
	v_pk_fma_f32 v[124:125], v[106:107], v[106:107], v[2:3] op_sel_hi:[1,1,0]
	v_mul_f32_e32 v2, v109, v109
	v_lshlrev_b32_e32 v92, 16, v86
	v_and_b32_e32 v94, 0xffff0000, v86
	v_mul_f32_e32 v86, v104, v104
	v_mul_f32_e32 v100, v105, v105
	v_pk_fma_f32 v[130:131], v[108:109], v[108:109], v[2:3] op_sel_hi:[1,1,0]
	v_mov_b32_e32 v125, v86
	v_mov_b32_e32 v131, v100
	v_and_b32_e32 v99, 0xffff0000, v91
	v_and_b32_e32 v98, 0xffff0000, v90
	v_pk_add_f32 v[124:125], v[124:125], v[130:131]
	v_lshlrev_b32_e32 v97, 16, v91
	v_lshlrev_b32_e32 v96, 16, v90
	v_pk_add_f32 v[122:123], v[122:123], v[124:125]
	v_pk_mul_f32 v[124:125], v[98:99], v[98:99]
	v_lshlrev_b32_e32 v93, 16, v87
	v_pk_fma_f32 v[124:125], v[96:97], v[96:97], v[124:125]
	v_and_b32_e32 v95, 0xffff0000, v87
	v_lshlrev_b32_e32 v87, 16, v84
	v_pk_add_f32 v[124:125], v[124:125], v[124:125] op_sel:[0,1] op_sel_hi:[1,0]
	v_pk_add_f32 v[122:123], v[122:123], v[122:123] op_sel:[0,1] op_sel_hi:[1,0]
	v_pk_mul_f32 v[130:131], v[94:95], v[94:95]
	v_mov_b32_e32 v86, v122
	v_mov_b32_e32 v132, v124
	v_mov_b32_e32 v133, v87
	v_lshlrev_b32_e32 v90, 16, v83
	v_and_b32_e32 v91, 0xffff0000, v83
	v_and_b32_e32 v83, 0xffff0000, v84
	v_pk_fma_f32 v[130:131], v[92:93], v[92:93], v[130:131]
	v_pk_add_f32 v[122:123], v[122:123], v[124:125]
	v_pk_mul_f32 v[124:125], v[86:87], v[132:133]
	v_mul_f32_e32 v2, v83, v83
	v_mov_b32_e32 v123, v125
	v_pk_add_f32 v[124:125], v[130:131], v[130:131] op_sel:[0,1] op_sel_hi:[1,0]
	v_lshlrev_b32_e32 v84, 16, v85
	v_mov_b32_e32 v125, v2
	v_mul_f32_e32 v2, v89, v89
	v_and_b32_e32 v85, 0xffff0000, v85
	v_pk_add_f32 v[122:123], v[122:123], v[124:125]
	v_pk_fma_f32 v[124:125], v[88:89], v[88:89], v[2:3] op_sel_hi:[1,1,0]
	v_mul_f32_e32 v2, v91, v91
	v_mul_f32_e32 v82, v84, v84
	v_mul_f32_e32 v100, v85, v85
	v_pk_fma_f32 v[130:131], v[90:91], v[90:91], v[2:3] op_sel_hi:[1,1,0]
	v_mov_b32_e32 v125, v82
	v_mov_b32_e32 v131, v100
	v_pk_add_f32 v[124:125], v[124:125], v[130:131]
	s_add_i32 s3, s0, 0xffffe000
	v_pk_add_f32 v[122:123], v[122:123], v[124:125]
	s_cmpk_lt_i32 s0, 0x2000
	v_add_f32_e32 v2, v122, v123
	ds_bpermute_b32 v82, v1, v2
	s_cselect_b32 s0, s0, s3
	s_cselect_b32 s3, 0, 0x4000000
	s_cselect_b32 s1, s1, 0
	s_add_u32 s3, s90, s3
	s_waitcnt lgkmcnt(0)
	v_add_f32_e32 v2, v2, v82
	ds_bpermute_b32 v82, v114, v2
	s_addc_u32 s9, s91, 0
	s_lshl_b64 s[10:11], s[0:1], 13
	v_and_b32_e32 v131, 0xffff0000, v80
	s_waitcnt lgkmcnt(0)
	v_add_f32_e32 v2, v2, v82
	ds_bpermute_b32 v82, v115, v2
	s_waitcnt lgkmcnt(0)
	v_add_f32_e32 v2, v2, v82
	ds_bpermute_b32 v82, v116, v2
	s_waitcnt lgkmcnt(0)
	v_add_f32_e32 v2, v2, v82
	ds_bpermute_b32 v82, v117, v2
	s_waitcnt lgkmcnt(0)
	v_add_f32_e32 v2, v2, v82
	ds_bpermute_b32 v82, v118, v2
	s_waitcnt lgkmcnt(0)
	v_add_f32_e32 v2, v2, v82
	v_fmamk_f32 v2, v2, 0x3a000000, v119
	v_mul_f32_e32 v82, 0x4f800000, v2
	v_cmp_gt_f32_e32 vcc, s7, v2
	s_nop 1
	v_cndmask_b32_e32 v2, v2, v82, vcc
	v_sqrt_f32_e32 v82, v2
	s_nop 0
	v_add_u32_e32 v86, -1, v82
	v_fma_f32 v100, -v86, v82, v2
	v_cmp_ge_f32_e64 s[0:1], 0, v100
	v_add_u32_e32 v100, 1, v82
	s_nop 0
	v_cndmask_b32_e64 v86, v82, v86, s[0:1]
	v_fma_f32 v82, -v100, v82, v2
	v_cmp_lt_f32_e64 s[0:1], 0, v82
	s_nop 1
	v_cndmask_b32_e64 v82, v86, v100, s[0:1]
	v_mul_f32_e32 v86, 0x37800000, v82
	v_cndmask_b32_e32 v82, v82, v86, vcc
	v_cmp_class_f32_e32 vcc, v2, v120
	s_nop 1
	v_cndmask_b32_e32 v82, v82, v2, vcc
	v_div_scale_f32 v86, s[0:1], v82, v82, 1.0
	v_rcp_f32_e32 v100, v86
	s_add_u32 s0, s3, s10
	s_addc_u32 s1, s9, s11
	v_lshlrev_b32_e32 v2, 4, v0
	v_fma_f32 v102, -v86, v100, 1.0
	v_fmac_f32_e32 v100, v102, v100
	v_div_scale_f32 v102, vcc, 1.0, v82, 1.0
	v_mul_f32_e32 v121, v102, v100
	v_fma_f32 v130, -v86, v121, v102
	v_fmac_f32_e32 v121, v130, v100
	v_fma_f32 v86, -v86, v121, v102
	v_div_fmas_f32 v86, v86, v100, v121
	v_div_fixup_f32 v86, v86, v82, 1.0
	v_lshlrev_b32_e32 v130, 16, v80
	v_lshlrev_b32_e32 v80, 16, v81
	v_and_b32_e32 v81, 0xffff0000, v81
	v_pk_mul_f32 v[126:127], v[86:87], v[126:127] op_sel_hi:[0,1]
	v_pk_mul_f32 v[128:129], v[86:87], v[128:129] op_sel_hi:[0,1]
	v_pk_fma_f32 v[124:125], v[136:137], v[128:129], v[80:81]
	v_pk_fma_f32 v[122:123], v[134:135], v[126:127], v[130:131]
	global_store_dwordx4 v2, v[122:125], s[0:1] nt
	v_lshlrev_b32_e32 v80, 16, v78
	v_and_b32_e32 v81, 0xffff0000, v78
	v_lshlrev_b32_e32 v126, 16, v79
	v_and_b32_e32 v127, 0xffff0000, v79
	v_mov_b32_e32 v78, v111
	v_mov_b32_e32 v79, v113
	v_mov_b32_e32 v111, v112
	v_pk_mul_f32 v[112:113], v[86:87], v[78:79] op_sel_hi:[0,1]
	v_pk_mul_f32 v[78:79], v[86:87], v[110:111] op_sel_hi:[0,1]
	v_lshlrev_b32_e32 v110, 16, v76
	v_and_b32_e32 v111, 0xffff0000, v76
	v_pk_mul_f32 v[108:109], v[86:87], v[108:109] op_sel_hi:[0,1]
	v_mov_b32_e32 v100, v103
	v_pk_mul_f32 v[102:103], v[86:87], v[104:105] op_sel_hi:[0,1]
	v_mov_b32_e32 v82, v87
	v_pk_fma_f32 v[78:79], v[138:139], v[78:79], v[80:81]
	v_pk_fma_f32 v[80:81], v[140:141], v[112:113], v[126:127]
	global_store_dwordx4 v2, v[78:81], s[0:1] offset:1024 nt
	v_lshlrev_b32_e32 v112, 16, v77
	v_and_b32_e32 v113, 0xffff0000, v77
	v_pk_mul_f32 v[76:77], v[86:87], v[106:107] op_sel_hi:[0,1]
	v_lshlrev_b32_e32 v106, 16, v75
	v_and_b32_e32 v107, 0xffff0000, v75
	v_pk_fma_f32 v[76:77], v[142:143], v[76:77], v[110:111]
	v_pk_fma_f32 v[78:79], v[144:145], v[108:109], v[112:113]
	global_store_dwordx4 v2, v[76:79], s[0:1] offset:2048 nt
	v_lshlrev_b32_e32 v80, 16, v74
	v_and_b32_e32 v81, 0xffff0000, v74
	v_pk_mul_f32 v[74:75], v[86:87], v[100:101] op_sel_hi:[0,1]
	v_pk_fma_f32 v[74:75], v[146:147], v[74:75], v[80:81]
	v_pk_fma_f32 v[76:77], v[148:149], v[102:103], v[106:107]
	global_store_dwordx4 v2, v[74:77], s[0:1] offset:3072 nt
	v_lshlrev_b32_e32 v78, 16, v72
	v_and_b32_e32 v79, 0xffff0000, v72
	v_lshlrev_b32_e32 v80, 16, v73
	v_and_b32_e32 v81, 0xffff0000, v73
	v_mov_b32_e32 v72, v97
	v_mov_b32_e32 v73, v99
	v_mov_b32_e32 v97, v98
	v_lshl_add_u64 v[98:99], s[0:1], 0, v[2:3]
	v_add_co_u32_e32 v98, vcc, s8, v98
	v_pk_mul_f32 v[100:101], v[86:87], v[72:73] op_sel_hi:[0,1]
	v_pk_mul_f32 v[72:73], v[86:87], v[96:97] op_sel_hi:[0,1]
	v_addc_co_u32_e32 v99, vcc, 0, v99, vcc
	s_andn2_b64 vcc, exec, s[4:5]
	v_pk_fma_f32 v[72:73], v[72:73], v[150:151], v[78:79]
	v_pk_fma_f32 v[74:75], v[100:101], v[152:153], v[80:81]
	global_store_dwordx4 v[98:99], v[72:75], off nt
	v_lshlrev_b32_e32 v76, 16, v70
	v_and_b32_e32 v77, 0xffff0000, v70
	v_lshlrev_b32_e32 v78, 16, v71
	v_and_b32_e32 v79, 0xffff0000, v71
	v_mov_b32_e32 v70, v93
	v_mov_b32_e32 v71, v95
	v_mov_b32_e32 v93, v94
	v_pk_mul_f32 v[80:81], v[86:87], v[70:71] op_sel_hi:[0,1]
	v_pk_mul_f32 v[70:71], v[86:87], v[92:93] op_sel_hi:[0,1]
	v_pk_fma_f32 v[70:71], v[70:71], v[154:155], v[76:77]
	v_pk_fma_f32 v[72:73], v[80:81], v[156:157], v[78:79]
	global_store_dwordx4 v[98:99], v[70:73], off offset:1024 nt
	v_lshlrev_b32_e32 v74, 16, v68
	v_and_b32_e32 v75, 0xffff0000, v68
	v_lshlrev_b32_e32 v76, 16, v69
	v_and_b32_e32 v77, 0xffff0000, v69
	v_pk_mul_f32 v[78:79], v[86:87], v[90:91] op_sel_hi:[0,1]
	v_pk_mul_f32 v[68:69], v[86:87], v[88:89] op_sel_hi:[0,1]
	v_pk_fma_f32 v[68:69], v[68:69], v[158:159], v[74:75]
	v_pk_fma_f32 v[70:71], v[78:79], v[160:161], v[76:77]
	global_store_dwordx4 v[98:99], v[68:71], off offset:2048 nt
	v_lshlrev_b32_e32 v72, 16, v66
	v_and_b32_e32 v73, 0xffff0000, v66
	v_lshlrev_b32_e32 v74, 16, v67
	v_and_b32_e32 v75, 0xffff0000, v67
	v_pk_mul_f32 v[76:77], v[86:87], v[84:85] op_sel_hi:[0,1]
	v_pk_mul_f32 v[66:67], v[86:87], v[82:83] op_sel_hi:[0,1]
	v_pk_fma_f32 v[66:67], v[66:67], v[162:163], v[72:73]
	v_pk_fma_f32 v[68:69], v[76:77], v[164:165], v[74:75]
	global_store_dwordx4 v[98:99], v[66:69], off offset:3072 nt
	s_cbranch_vccnz .LBB0_1292
	s_nop 0
	v_mov_b32_e32 v68, v59
	v_mov_b32_e32 v69, v63
	v_mov_b32_e32 v66, v58
	v_mov_b32_e32 v67, v62
	v_pk_mul_f32 v[68:69], v[68:69], v[68:69]
	v_mov_b32_e32 v70, v61
	v_mov_b32_e32 v71, v65
	v_pk_fma_f32 v[66:67], v[66:67], v[66:67], v[68:69]
	v_mov_b32_e32 v68, v60
	v_mov_b32_e32 v69, v64
	v_pk_mul_f32 v[70:71], v[70:71], v[70:71]
	s_ashr_i32 s0, s2, 31
	v_pk_fma_f32 v[68:69], v[68:69], v[68:69], v[70:71]
	v_pk_mul_f32 v[70:71], v[52:53], v[52:53]
	v_pk_add_f32 v[66:67], v[66:67], v[68:69]
	v_pk_mul_f32 v[68:69], v[54:55], v[54:55]
	v_pk_add_f32 v[66:67], v[66:67], v[66:67] op_sel_hi:[0,1]
	v_pk_mov_b32 v[72:73], v[70:71], v[68:69] op_sel:[1,0]
	v_mov_b32_e32 v71, v69
	v_mul_f32_e32 v66, v46, v46
	v_pk_add_f32 v[68:69], v[72:73], v[70:71]
	v_pk_fma_f32 v[70:71], v[46:47], v[46:47], v[66:67] op_sel_hi:[1,1,0]
	v_mul_f32_e32 v66, v48, v48
	v_pk_add_f32 v[68:69], v[68:69], v[68:69] op_sel_hi:[0,1]
	v_pk_fma_f32 v[72:73], v[48:49], v[48:49], v[66:67] op_sel_hi:[1,1,0]
	v_mul_f32_e32 v70, v40, v40
	v_mul_f32_e32 v72, v41, v41
	v_mul_f32_e32 v68, v42, v42
	v_mul_f32_e32 v66, v43, v43
	v_pk_add_f32 v[70:71], v[70:71], v[72:73]
	v_pk_add_f32 v[66:67], v[68:69], v[66:67]
	v_pk_mul_f32 v[68:69], v[36:37], v[36:37]
	v_pk_add_f32 v[66:67], v[70:71], v[66:67]
	v_pk_mul_f32 v[70:71], v[34:35], v[34:35]
	v_pk_add_f32 v[66:67], v[66:67], v[66:67] op_sel_hi:[0,1]
	v_pk_mov_b32 v[72:73], v[70:71], v[68:69] op_sel:[1,0]
	v_mov_b32_e32 v71, v69
	v_mul_f32_e32 v66, v28, v28
	v_pk_add_f32 v[68:69], v[72:73], v[70:71]
	v_pk_fma_f32 v[70:71], v[28:29], v[28:29], v[66:67] op_sel_hi:[1,1,0]
	v_mul_f32_e32 v66, v30, v30
	v_pk_add_f32 v[68:69], v[68:69], v[68:69] op_sel_hi:[0,1]
	v_pk_fma_f32 v[72:73], v[30:31], v[30:31], v[66:67] op_sel_hi:[1,1,0]
	v_mul_f32_e32 v70, v22, v22
	v_mul_f32_e32 v72, v23, v23
	v_mul_f32_e32 v68, v24, v24
	v_mul_f32_e32 v66, v25, v25
	v_pk_add_f32 v[70:71], v[70:71], v[72:73]
	v_pk_add_f32 v[66:67], v[68:69], v[66:67]
	s_add_i32 s1, s2, 0xffffe000
	v_pk_add_f32 v[66:67], v[70:71], v[66:67]
	s_cmpk_lt_i32 s2, 0x2000
	v_add_f32_e32 v70, v66, v67
	ds_bpermute_b32 v71, v1, v70
	s_cselect_b32 s5, s0, 0
	s_cselect_b32 s0, 0, 0x4000000
	s_cselect_b32 s4, s2, s1
	s_add_u32 s3, s90, s0
	s_waitcnt lgkmcnt(0)
	v_add_f32_e32 v70, v70, v71
	ds_bpermute_b32 v71, v114, v70
	s_addc_u32 s9, s91, 0
	s_waitcnt lgkmcnt(0)
	v_add_f32_e32 v70, v70, v71
	ds_bpermute_b32 v71, v115, v70
	s_waitcnt lgkmcnt(0)
	v_add_f32_e32 v70, v70, v71
	ds_bpermute_b32 v71, v116, v70
	s_waitcnt lgkmcnt(0)
	v_add_f32_e32 v70, v70, v71
	ds_bpermute_b32 v71, v117, v70
	s_waitcnt lgkmcnt(0)
	v_add_f32_e32 v70, v70, v71
	ds_bpermute_b32 v71, v118, v70
	s_waitcnt lgkmcnt(0)
	v_add_f32_e32 v70, v70, v71
	v_fmamk_f32 v70, v70, 0x3a000000, v119
	v_mul_f32_e32 v71, 0x4f800000, v70
	v_cmp_gt_f32_e32 vcc, s7, v70
	s_nop 1
	v_cndmask_b32_e32 v70, v70, v71, vcc
	v_sqrt_f32_e32 v71, v70
	s_nop 0
	v_add_u32_e32 v72, -1, v71
	v_fma_f32 v73, -v72, v71, v70
	v_cmp_ge_f32_e64 s[0:1], 0, v73
	v_add_u32_e32 v73, 1, v71
	s_nop 0
	v_cndmask_b32_e64 v72, v71, v72, s[0:1]
	v_fma_f32 v71, -v73, v71, v70
	v_cmp_lt_f32_e64 s[0:1], 0, v71
	s_nop 1
	v_cndmask_b32_e64 v71, v72, v73, s[0:1]
	v_mul_f32_e32 v72, 0x37800000, v71
	v_cndmask_b32_e32 v71, v71, v72, vcc
	v_cmp_class_f32_e32 vcc, v70, v120
	s_nop 1
	v_cndmask_b32_e32 v70, v71, v70, vcc
	v_div_scale_f32 v71, s[0:1], v70, v70, 1.0
	v_rcp_f32_e32 v72, v71
	s_lshl_b64 s[0:1], s[4:5], 13
	s_add_u32 s0, s3, s0
	s_addc_u32 s1, s9, s1
	v_fma_f32 v73, -v71, v72, 1.0
	v_fmac_f32_e32 v72, v73, v72
	v_div_scale_f32 v73, vcc, 1.0, v70, 1.0
	v_mul_f32_e32 v74, v73, v72
	v_fma_f32 v75, -v71, v74, v73
	v_fmac_f32_e32 v74, v75, v72
	v_fma_f32 v71, -v71, v74, v73
	v_div_fmas_f32 v71, v71, v72, v74
	v_div_fixup_f32 v70, v71, v70, 1.0
	v_lshlrev_b32_e32 v72, 16, v56
	v_and_b32_e32 v73, 0xffff0000, v56
	v_lshlrev_b32_e32 v56, 16, v57
	v_and_b32_e32 v57, 0xffff0000, v57
	v_pk_mul_f32 v[62:63], v[62:63], v[70:71] op_sel_hi:[1,0]
	v_pk_mul_f32 v[64:65], v[64:65], v[70:71] op_sel_hi:[1,0]
	v_pk_fma_f32 v[62:63], v[134:135], v[62:63], v[72:73]
	v_pk_fma_f32 v[64:65], v[136:137], v[64:65], v[56:57]
	global_store_dwordx4 v2, v[62:65], s[0:1] nt
	v_lshlrev_b32_e32 v56, 16, v50
	v_and_b32_e32 v57, 0xffff0000, v50
	v_lshlrev_b32_e32 v50, 16, v51
	v_and_b32_e32 v51, 0xffff0000, v51
	v_pk_mul_f32 v[60:61], v[60:61], v[70:71] op_sel_hi:[1,0]
	v_pk_mul_f32 v[58:59], v[58:59], v[70:71] op_sel_hi:[1,0]
	v_pk_mul_f32 v[54:55], v[54:55], v[70:71] op_sel_hi:[1,0]
	v_pk_mul_f32 v[52:53], v[52:53], v[70:71] op_sel_hi:[1,0]
	v_pk_mul_f32 v[48:49], v[48:49], v[70:71] op_sel_hi:[1,0]
	v_pk_mul_f32 v[46:47], v[46:47], v[70:71] op_sel_hi:[1,0]
	v_pk_mul_f32 v[42:43], v[42:43], v[70:71] op_sel_hi:[1,0]
	v_pk_mul_f32 v[40:41], v[40:41], v[70:71] op_sel_hi:[1,0]
	v_pk_mul_f32 v[36:37], v[36:37], v[70:71] op_sel_hi:[1,0]
	v_pk_mul_f32 v[34:35], v[34:35], v[70:71] op_sel_hi:[1,0]
	v_pk_mul_f32 v[30:31], v[30:31], v[70:71] op_sel_hi:[1,0]
	v_pk_mul_f32 v[28:29], v[28:29], v[70:71] op_sel_hi:[1,0]
	v_pk_mul_f32 v[24:25], v[24:25], v[70:71] op_sel_hi:[1,0]
	v_pk_fma_f32 v[56:57], v[138:139], v[58:59], v[56:57]
	v_pk_fma_f32 v[58:59], v[140:141], v[60:61], v[50:51]
	global_store_dwordx4 v2, v[56:59], s[0:1] offset:1024 nt
	v_lshlrev_b32_e32 v50, 16, v44
	v_and_b32_e32 v51, 0xffff0000, v44
	v_lshlrev_b32_e32 v44, 16, v45
	v_and_b32_e32 v45, 0xffff0000, v45
	v_pk_fma_f32 v[50:51], v[142:143], v[52:53], v[50:51]
	v_pk_fma_f32 v[52:53], v[144:145], v[54:55], v[44:45]
	global_store_dwordx4 v2, v[50:53], s[0:1] offset:2048 nt
	v_lshlrev_b32_e32 v44, 16, v38
	v_and_b32_e32 v45, 0xffff0000, v38
	v_lshlrev_b32_e32 v38, 16, v39
	v_and_b32_e32 v39, 0xffff0000, v39
	v_pk_fma_f32 v[44:45], v[146:147], v[46:47], v[44:45]
	v_pk_fma_f32 v[46:47], v[148:149], v[48:49], v[38:39]
	global_store_dwordx4 v2, v[44:47], s[0:1] offset:3072 nt
	v_lshl_add_u64 v[48:49], s[0:1], 0, v[2:3]
	v_lshlrev_b32_e32 v38, 16, v32
	v_and_b32_e32 v39, 0xffff0000, v32
	v_lshlrev_b32_e32 v32, 16, v33
	v_and_b32_e32 v33, 0xffff0000, v33
	v_add_co_u32_e32 v48, vcc, s8, v48
	v_pk_fma_f32 v[38:39], v[40:41], v[150:151], v[38:39]
	v_addc_co_u32_e32 v49, vcc, 0, v49, vcc
	v_pk_fma_f32 v[40:41], v[42:43], v[152:153], v[32:33]
	global_store_dwordx4 v[48:49], v[38:41], off nt
	v_lshlrev_b32_e32 v32, 16, v26
	v_and_b32_e32 v33, 0xffff0000, v26
	v_lshlrev_b32_e32 v26, 16, v27
	v_and_b32_e32 v27, 0xffff0000, v27
	v_pk_fma_f32 v[32:33], v[34:35], v[154:155], v[32:33]
	v_pk_fma_f32 v[34:35], v[36:37], v[156:157], v[26:27]
	global_store_dwordx4 v[48:49], v[32:35], off offset:1024 nt
	v_lshlrev_b32_e32 v26, 16, v20
	v_and_b32_e32 v27, 0xffff0000, v20
	v_lshlrev_b32_e32 v20, 16, v21
	v_and_b32_e32 v21, 0xffff0000, v21
	v_pk_fma_f32 v[26:27], v[28:29], v[158:159], v[26:27]
	v_pk_fma_f32 v[28:29], v[30:31], v[160:161], v[20:21]
	global_store_dwordx4 v[48:49], v[26:29], off offset:2048 nt
	v_lshlrev_b32_e32 v20, 16, v18
	v_and_b32_e32 v21, 0xffff0000, v18
	v_lshlrev_b32_e32 v30, 16, v19
	v_and_b32_e32 v31, 0xffff0000, v19
	v_pk_mul_f32 v[18:19], v[22:23], v[70:71] op_sel_hi:[1,0]
	v_pk_fma_f32 v[18:19], v[18:19], v[162:163], v[20:21]
	v_pk_fma_f32 v[20:21], v[24:25], v[164:165], v[30:31]
	global_store_dwordx4 v[48:49], v[18:21], off offset:3072 nt
	s_branch .LBB0_1292
